# strategy 2 (epilogue de-serialisation) on the context-row GEMM of the FFN-out phases: gate / residual / gain loads issued after the last K chunk's barrier
# baseline (speedup 1.0000x reference)
.LBB0_365:
	v_mov_b32_e32 v28, v176
	s_and_b32 s14, s21, 0x1e0
	v_add_u32_e32 v8, s1, v28
	s_and_b32 s15, s19, 0xffffffc0
	s_bitset1_b32 s14, 14
	s_sub_i32 s26, s15, 32
	v_lshlrev_b32_e32 v0, 4, v28
	v_ashrrev_i32_e32 v9, 5, v8
	v_and_b32_e32 v0, 0x1f0, v0
	v_mov_b32_e32 v10, s26
	v_mov_b32_e32 v11, s14
	v_cmp_gt_i32_e32 vcc, 32, v9
	v_lshl_add_u64 v[2:3], s[10:11], 0, v[0:1]
	v_lshl_add_u64 v[4:5], s[36:37], 0, v[0:1]
	v_cndmask_b32_e32 v6, v10, v11, vcc
	v_add_u32_e32 v12, v6, v9
	v_cndmask_b32_e32 v7, v3, v5, vcc
	v_cndmask_b32_e32 v6, v2, v4, vcc
	v_mad_i64_i32 v[18:19], s[26:27], v12, s22, v[6:7]
	v_add_u32_e32 v6, 0x200, v8
	v_ashrrev_i32_e32 v12, 5, v6
	v_cmp_gt_i32_e32 vcc, 32, v12
	v_add_u32_e32 v0, 0, v0
	s_or_b32 s15, s15, s17
	v_cndmask_b32_e32 v6, v10, v11, vcc
	v_add_u32_e32 v13, v6, v12
	v_cndmask_b32_e32 v7, v3, v5, vcc
	v_cndmask_b32_e32 v6, v2, v4, vcc
	v_mad_i64_i32 v[16:17], s[26:27], v13, s22, v[6:7]
	v_add_u32_e32 v6, 0x400, v8
	v_ashrrev_i32_e32 v13, 5, v6
	v_cmp_gt_i32_e32 vcc, 32, v13
	s_add_i32 s14, s14, s16
	s_nop 0
	v_cndmask_b32_e32 v6, v10, v11, vcc
	v_add_u32_e32 v14, v6, v13
	v_cndmask_b32_e32 v7, v3, v5, vcc
	v_cndmask_b32_e32 v6, v2, v4, vcc
	v_mad_i64_i32 v[20:21], s[26:27], v14, s22, v[6:7]
	v_add_u32_e32 v6, 0x600, v8
	v_ashrrev_i32_e32 v14, 5, v6
	v_cmp_gt_i32_e32 vcc, 32, v14
	s_nop 1
	v_cndmask_b32_e32 v6, v10, v11, vcc
	v_add_u32_e32 v15, v6, v14
	v_cndmask_b32_e32 v7, v3, v5, vcc
	v_cndmask_b32_e32 v6, v2, v4, vcc
	v_mad_i64_i32 v[22:23], s[26:27], v15, s22, v[6:7]
	v_add_u32_e32 v6, 0x800, v8
	v_ashrrev_i32_e32 v15, 5, v6
	v_cmp_gt_i32_e32 vcc, 32, v15
	s_nop 1
	v_cndmask_b32_e32 v6, v10, v11, vcc
	v_add_u32_e32 v24, v6, v15
	v_cndmask_b32_e32 v7, v3, v5, vcc
	v_cndmask_b32_e32 v6, v2, v4, vcc
	v_mad_i64_i32 v[24:25], s[26:27], v24, s22, v[6:7]
	v_add_u32_e32 v6, 0xa00, v8
	v_ashrrev_i32_e32 v29, 5, v6
	v_cmp_gt_i32_e32 vcc, 32, v29
	s_nop 1
	v_cndmask_b32_e32 v6, v10, v11, vcc
	v_add_u32_e32 v6, v6, v29
	v_cndmask_b32_e32 v3, v3, v5, vcc
	v_cndmask_b32_e32 v2, v2, v4, vcc
	v_mad_i64_i32 v[26:27], s[26:27], v6, s22, v[2:3]
	global_load_dwordx4 v[136:139], v[18:19], off
	global_load_dwordx4 v[140:143], v[16:17], off
	global_load_dwordx4 v[144:147], v[20:21], off
	global_load_dwordx4 v[148:151], v[22:23], off
	global_load_dwordx4 v[152:155], v[24:25], off
	global_load_dwordx4 v[156:159], v[26:27], off
	global_load_dwordx4 v[178:181], v[18:19], off offset:512
	global_load_dwordx4 v[182:185], v[16:17], off offset:512
	global_load_dwordx4 v[186:189], v[20:21], off offset:512
	global_load_dwordx4 v[190:193], v[22:23], off offset:512
	global_load_dwordx4 v[194:197], v[24:25], off offset:512
	global_load_dwordx4 v[198:201], v[26:27], off offset:512
	global_load_dwordx4 v[206:209], v[18:19], off offset:1024
	global_load_dwordx4 v[210:213], v[16:17], off offset:1024
	global_load_dwordx4 v[214:217], v[20:21], off offset:1024
	global_load_dwordx4 v[218:221], v[22:23], off offset:1024
	global_load_dwordx4 v[120:123], v[24:25], off offset:1024
	global_load_dwordx4 v[124:127], v[26:27], off offset:1024
	v_mov_b32_e32 v112, 0x1000
	v_mov_b32_e32 v113, 0
	v_lshl_add_u64 v[128:129], v[18:19], 0, v[112:113]
	v_lshl_add_u64 v[130:131], v[16:17], 0, v[112:113]
	v_lshl_add_u64 v[132:133], v[20:21], 0, v[112:113]
	v_lshl_add_u64 v[106:107], v[22:23], 0, v[112:113]
	v_lshl_add_u64 v[108:109], v[24:25], 0, v[112:113]
	v_lshl_add_u64 v[110:111], v[26:27], 0, v[112:113]
	v_mad_u64_u32 v[4:5], s[26:27], v9, s23, v[0:1]
	v_mad_u64_u32 v[6:7], s[26:27], v12, s23, v[0:1]
	v_mad_u64_u32 v[8:9], s[26:27], v13, s23, v[0:1]
	v_mad_u64_u32 v[10:11], s[26:27], v14, s23, v[0:1]
	v_mad_u64_u32 v[12:13], s[26:27], v15, s23, v[0:1]
	v_mad_u64_u32 v[14:15], s[26:27], v29, s23, v[0:1]
	s_barrier
	v_and_b32_e32 v0, 15, v28
	v_and_b32_e32 v2, -16, v28
	v_add_u32_e32 v2, 0, v2
	v_or_b32_e32 v5, s18, v0
	v_mad_u32_u24 v5, v5, s23, v2
	v_or_b32_e32 v3, s16, v0
	v_mad_u64_u32 v[2:3], s[26:27], v3, s23, v[2:3]
	v_ashrrev_i32_e32 v3, 2, v28
	v_and_b32_e32 v3, -4, v3
	v_or_b32_e32 v0, s14, v0
	s_waitcnt vmcnt(17)
	ds_write_b128 v4, v[136:139]
	s_waitcnt vmcnt(16)
	ds_write_b128 v6, v[140:143]
	s_waitcnt vmcnt(15)
	ds_write_b128 v8, v[144:147]
	s_waitcnt vmcnt(14)
	ds_write_b128 v10, v[148:151]
	s_waitcnt vmcnt(13)
	ds_write_b128 v12, v[152:155]
	s_waitcnt vmcnt(12)
	ds_write_b128 v14, v[156:159]
	s_waitcnt lgkmcnt(0)
	s_barrier
	global_load_dwordx4 v[136:139], v[18:19], off offset:1536
	global_load_dwordx4 v[140:143], v[16:17], off offset:1536
	global_load_dwordx4 v[144:147], v[20:21], off offset:1536
	global_load_dwordx4 v[148:151], v[22:23], off offset:1536
	global_load_dwordx4 v[152:155], v[24:25], off offset:1536
	global_load_dwordx4 v[156:159], v[26:27], off offset:1536
	ds_read_b128 v[54:57], v5
	ds_read_b128 v[58:61], v5 offset:64
	ds_read_b128 v[62:65], v2
	ds_read_b128 v[66:69], v2 offset:64
	s_waitcnt lgkmcnt(1)
	v_mfma_f32_16x16x32_f16 v[54:57], v[54:57], v[62:65], 0
	ds_read_b128 v[62:65], v5 offset:128
	ds_read_b128 v[70:73], v5 offset:192
	s_waitcnt lgkmcnt(2)
	v_mfma_f32_16x16x32_f16 v[54:57], v[58:61], v[66:69], v[54:57]
	ds_read_b128 v[58:61], v2 offset:128
	ds_read_b128 v[66:69], v2 offset:192
	s_waitcnt lgkmcnt(1)
	v_mfma_f32_16x16x32_f16 v[54:57], v[62:65], v[58:61], v[54:57]
	ds_read_b128 v[58:61], v5 offset:256
	ds_read_b128 v[62:65], v5 offset:320
	s_waitcnt lgkmcnt(2)
	v_mfma_f32_16x16x32_f16 v[54:57], v[70:73], v[66:69], v[54:57]
	ds_read_b128 v[66:69], v2 offset:256
	ds_read_b128 v[70:73], v2 offset:320
	ds_read_b128 v[74:77], v5 offset:384
	s_waitcnt lgkmcnt(2)
	v_mfma_f32_16x16x32_f16 v[54:57], v[58:61], v[66:69], v[54:57]
	ds_read_b128 v[58:61], v2 offset:384
	ds_read_b128 v[66:69], v2 offset:448
	ds_read_b128 v[78:81], v5 offset:448
	s_waitcnt lgkmcnt(0)
	s_barrier
	s_waitcnt vmcnt(17)
	ds_write_b128 v4, v[178:181]
	s_waitcnt vmcnt(16)
	ds_write_b128 v6, v[182:185]
	s_waitcnt vmcnt(15)
	ds_write_b128 v8, v[186:189]
	s_waitcnt vmcnt(14)
	ds_write_b128 v10, v[190:193]
	s_waitcnt vmcnt(13)
	ds_write_b128 v12, v[194:197]
	s_waitcnt vmcnt(12)
	ds_write_b128 v14, v[198:201]
	s_waitcnt lgkmcnt(0)
	s_barrier
	global_load_dwordx4 v[178:181], v[18:19], off offset:2048
	global_load_dwordx4 v[182:185], v[16:17], off offset:2048
	global_load_dwordx4 v[186:189], v[20:21], off offset:2048
	global_load_dwordx4 v[190:193], v[22:23], off offset:2048
	global_load_dwordx4 v[194:197], v[24:25], off offset:2048
	global_load_dwordx4 v[198:201], v[26:27], off offset:2048
	v_mfma_f32_16x16x32_f16 v[54:57], v[62:65], v[70:73], v[54:57]
	v_mfma_f32_16x16x32_f16 v[54:57], v[74:77], v[58:61], v[54:57]
	ds_read_b128 v[58:61], v5
	v_mfma_f32_16x16x32_f16 v[54:57], v[78:81], v[66:69], v[54:57]
	ds_read_b128 v[62:65], v5 offset:64
	ds_read_b128 v[66:69], v2
	ds_read_b128 v[70:73], v2 offset:64
	s_waitcnt lgkmcnt(1)
	v_mfma_f32_16x16x32_f16 v[54:57], v[58:61], v[66:69], v[54:57]
	ds_read_b128 v[58:61], v5 offset:128
	ds_read_b128 v[66:69], v5 offset:192
	s_waitcnt lgkmcnt(2)
	v_mfma_f32_16x16x32_f16 v[54:57], v[62:65], v[70:73], v[54:57]
	ds_read_b128 v[62:65], v2 offset:128
	ds_read_b128 v[70:73], v2 offset:192
	s_waitcnt lgkmcnt(1)
	v_mfma_f32_16x16x32_f16 v[54:57], v[58:61], v[62:65], v[54:57]
	ds_read_b128 v[58:61], v5 offset:256
	ds_read_b128 v[62:65], v5 offset:320
	s_waitcnt lgkmcnt(2)
	v_mfma_f32_16x16x32_f16 v[54:57], v[66:69], v[70:73], v[54:57]
	ds_read_b128 v[66:69], v2 offset:256
	ds_read_b128 v[70:73], v2 offset:320
	ds_read_b128 v[74:77], v5 offset:384
	s_waitcnt lgkmcnt(2)
	v_mfma_f32_16x16x32_f16 v[54:57], v[58:61], v[66:69], v[54:57]
	ds_read_b128 v[58:61], v2 offset:384
	ds_read_b128 v[66:69], v2 offset:448
	ds_read_b128 v[78:81], v5 offset:448
	s_waitcnt lgkmcnt(0)
	s_barrier
	s_waitcnt vmcnt(17)
	ds_write_b128 v4, v[206:209]
	s_waitcnt vmcnt(16)
	ds_write_b128 v6, v[210:213]
	s_waitcnt vmcnt(15)
	ds_write_b128 v8, v[214:217]
	s_waitcnt vmcnt(14)
	ds_write_b128 v10, v[218:221]
	s_waitcnt vmcnt(13)
	ds_write_b128 v12, v[120:123]
	s_waitcnt vmcnt(12)
	ds_write_b128 v14, v[124:127]
	s_waitcnt lgkmcnt(0)
	s_barrier
	global_load_dwordx4 v[206:209], v[18:19], off offset:2560
	global_load_dwordx4 v[210:213], v[16:17], off offset:2560
	global_load_dwordx4 v[214:217], v[20:21], off offset:2560
	global_load_dwordx4 v[218:221], v[22:23], off offset:2560
	global_load_dwordx4 v[120:123], v[24:25], off offset:2560
	global_load_dwordx4 v[124:127], v[26:27], off offset:2560
	v_mfma_f32_16x16x32_f16 v[54:57], v[62:65], v[70:73], v[54:57]
	v_mfma_f32_16x16x32_f16 v[54:57], v[74:77], v[58:61], v[54:57]
	ds_read_b128 v[58:61], v5
	v_mfma_f32_16x16x32_f16 v[54:57], v[78:81], v[66:69], v[54:57]
	ds_read_b128 v[62:65], v5 offset:64
	ds_read_b128 v[66:69], v2
	ds_read_b128 v[70:73], v2 offset:64
	s_waitcnt lgkmcnt(1)
	v_mfma_f32_16x16x32_f16 v[54:57], v[58:61], v[66:69], v[54:57]
	ds_read_b128 v[58:61], v5 offset:128
	ds_read_b128 v[66:69], v5 offset:192
	s_waitcnt lgkmcnt(2)
	v_mfma_f32_16x16x32_f16 v[54:57], v[62:65], v[70:73], v[54:57]
	ds_read_b128 v[62:65], v2 offset:128
	ds_read_b128 v[70:73], v2 offset:192
	s_waitcnt lgkmcnt(1)
	v_mfma_f32_16x16x32_f16 v[54:57], v[58:61], v[62:65], v[54:57]
	ds_read_b128 v[58:61], v5 offset:256
	ds_read_b128 v[62:65], v5 offset:320
	s_waitcnt lgkmcnt(2)
	v_mfma_f32_16x16x32_f16 v[54:57], v[66:69], v[70:73], v[54:57]
	ds_read_b128 v[66:69], v2 offset:256
	ds_read_b128 v[70:73], v2 offset:320
	ds_read_b128 v[74:77], v5 offset:384
	s_waitcnt lgkmcnt(2)
	v_mfma_f32_16x16x32_f16 v[54:57], v[58:61], v[66:69], v[54:57]
	ds_read_b128 v[58:61], v2 offset:384
	ds_read_b128 v[66:69], v2 offset:448
	ds_read_b128 v[78:81], v5 offset:448
	s_waitcnt lgkmcnt(0)
	s_barrier
	s_waitcnt vmcnt(17)
	ds_write_b128 v4, v[136:139]
	s_waitcnt vmcnt(16)
	ds_write_b128 v6, v[140:143]
	s_waitcnt vmcnt(15)
	ds_write_b128 v8, v[144:147]
	s_waitcnt vmcnt(14)
	ds_write_b128 v10, v[148:151]
	s_waitcnt vmcnt(13)
	ds_write_b128 v12, v[152:155]
	s_waitcnt vmcnt(12)
	ds_write_b128 v14, v[156:159]
	s_waitcnt lgkmcnt(0)
	s_barrier
	global_load_dwordx4 v[136:139], v[18:19], off offset:3072
	global_load_dwordx4 v[140:143], v[16:17], off offset:3072
	global_load_dwordx4 v[144:147], v[20:21], off offset:3072
	global_load_dwordx4 v[148:151], v[22:23], off offset:3072
	global_load_dwordx4 v[152:155], v[24:25], off offset:3072
	global_load_dwordx4 v[156:159], v[26:27], off offset:3072
	v_mfma_f32_16x16x32_f16 v[54:57], v[62:65], v[70:73], v[54:57]
	v_mfma_f32_16x16x32_f16 v[54:57], v[74:77], v[58:61], v[54:57]
	ds_read_b128 v[58:61], v5
	v_mfma_f32_16x16x32_f16 v[54:57], v[78:81], v[66:69], v[54:57]
	ds_read_b128 v[62:65], v5 offset:64
	ds_read_b128 v[66:69], v2
	ds_read_b128 v[70:73], v2 offset:64
	s_waitcnt lgkmcnt(1)
	v_mfma_f32_16x16x32_f16 v[54:57], v[58:61], v[66:69], v[54:57]
	ds_read_b128 v[58:61], v5 offset:128
	ds_read_b128 v[66:69], v5 offset:192
	s_waitcnt lgkmcnt(2)
	v_mfma_f32_16x16x32_f16 v[54:57], v[62:65], v[70:73], v[54:57]
	ds_read_b128 v[62:65], v2 offset:128
	ds_read_b128 v[70:73], v2 offset:192
	s_waitcnt lgkmcnt(1)
	v_mfma_f32_16x16x32_f16 v[54:57], v[58:61], v[62:65], v[54:57]
	ds_read_b128 v[58:61], v5 offset:256
	ds_read_b128 v[62:65], v5 offset:320
	s_waitcnt lgkmcnt(2)
	v_mfma_f32_16x16x32_f16 v[54:57], v[66:69], v[70:73], v[54:57]
	ds_read_b128 v[66:69], v2 offset:256
	ds_read_b128 v[70:73], v2 offset:320
	ds_read_b128 v[74:77], v5 offset:384
	s_waitcnt lgkmcnt(2)
	v_mfma_f32_16x16x32_f16 v[54:57], v[58:61], v[66:69], v[54:57]
	ds_read_b128 v[58:61], v2 offset:384
	ds_read_b128 v[66:69], v2 offset:448
	ds_read_b128 v[78:81], v5 offset:448
	s_waitcnt lgkmcnt(0)
	s_barrier
	s_waitcnt vmcnt(17)
	ds_write_b128 v4, v[178:181]
	s_waitcnt vmcnt(16)
	ds_write_b128 v6, v[182:185]
	s_waitcnt vmcnt(15)
	ds_write_b128 v8, v[186:189]
	s_waitcnt vmcnt(14)
	ds_write_b128 v10, v[190:193]
	s_waitcnt vmcnt(13)
	ds_write_b128 v12, v[194:197]
	s_waitcnt vmcnt(12)
	ds_write_b128 v14, v[198:201]
	s_waitcnt lgkmcnt(0)
	s_barrier
	global_load_dwordx4 v[178:181], v[18:19], off offset:3584
	global_load_dwordx4 v[182:185], v[16:17], off offset:3584
	global_load_dwordx4 v[186:189], v[20:21], off offset:3584
	global_load_dwordx4 v[190:193], v[22:23], off offset:3584
	global_load_dwordx4 v[194:197], v[24:25], off offset:3584
	global_load_dwordx4 v[198:201], v[26:27], off offset:3584
	v_mfma_f32_16x16x32_f16 v[54:57], v[62:65], v[70:73], v[54:57]
	v_mfma_f32_16x16x32_f16 v[54:57], v[74:77], v[58:61], v[54:57]
	ds_read_b128 v[58:61], v5
	v_mfma_f32_16x16x32_f16 v[54:57], v[78:81], v[66:69], v[54:57]
	ds_read_b128 v[62:65], v5 offset:64
	ds_read_b128 v[66:69], v2
	ds_read_b128 v[70:73], v2 offset:64
	s_waitcnt lgkmcnt(1)
	v_mfma_f32_16x16x32_f16 v[54:57], v[58:61], v[66:69], v[54:57]
	ds_read_b128 v[58:61], v5 offset:128
	ds_read_b128 v[66:69], v5 offset:192
	s_waitcnt lgkmcnt(2)
	v_mfma_f32_16x16x32_f16 v[54:57], v[62:65], v[70:73], v[54:57]
	ds_read_b128 v[62:65], v2 offset:128
	ds_read_b128 v[70:73], v2 offset:192
	s_waitcnt lgkmcnt(1)
	v_mfma_f32_16x16x32_f16 v[54:57], v[58:61], v[62:65], v[54:57]
	ds_read_b128 v[58:61], v5 offset:256
	ds_read_b128 v[62:65], v5 offset:320
	s_waitcnt lgkmcnt(2)
	v_mfma_f32_16x16x32_f16 v[54:57], v[66:69], v[70:73], v[54:57]
	ds_read_b128 v[66:69], v2 offset:256
	ds_read_b128 v[70:73], v2 offset:320
	ds_read_b128 v[74:77], v5 offset:384
	s_waitcnt lgkmcnt(2)
	v_mfma_f32_16x16x32_f16 v[54:57], v[58:61], v[66:69], v[54:57]
	ds_read_b128 v[58:61], v2 offset:384
	ds_read_b128 v[66:69], v2 offset:448
	ds_read_b128 v[78:81], v5 offset:448
	s_waitcnt lgkmcnt(0)
	s_barrier
	s_waitcnt vmcnt(17)
	ds_write_b128 v4, v[206:209]
	s_waitcnt vmcnt(16)
	ds_write_b128 v6, v[210:213]
	s_waitcnt vmcnt(15)
	ds_write_b128 v8, v[214:217]
	s_waitcnt vmcnt(14)
	ds_write_b128 v10, v[218:221]
	s_waitcnt vmcnt(13)
	ds_write_b128 v12, v[120:123]
	s_waitcnt vmcnt(12)
	ds_write_b128 v14, v[124:127]
	s_waitcnt lgkmcnt(0)
	s_barrier
	global_load_dwordx4 v[206:209], v[128:129], off
	global_load_dwordx4 v[210:213], v[130:131], off
	global_load_dwordx4 v[214:217], v[132:133], off
	global_load_dwordx4 v[218:221], v[106:107], off
	global_load_dwordx4 v[120:123], v[108:109], off
	global_load_dwordx4 v[124:127], v[110:111], off
	v_mfma_f32_16x16x32_f16 v[54:57], v[62:65], v[70:73], v[54:57]
	v_mfma_f32_16x16x32_f16 v[54:57], v[74:77], v[58:61], v[54:57]
	ds_read_b128 v[58:61], v5
	v_mfma_f32_16x16x32_f16 v[54:57], v[78:81], v[66:69], v[54:57]
	ds_read_b128 v[62:65], v2
	ds_read_b128 v[66:69], v2 offset:64
	ds_read_b128 v[70:73], v5 offset:64
	ds_read_b128 v[74:77], v2 offset:128
	ds_read_b128 v[78:81], v2 offset:192
	ds_read_b128 v[82:85], v5 offset:128
	ds_read_b128 v[86:89], v5 offset:192
	s_waitcnt lgkmcnt(6)
	v_mfma_f32_16x16x32_f16 v[54:57], v[58:61], v[62:65], v[54:57]
	ds_read_b128 v[58:61], v2 offset:256
	ds_read_b128 v[62:65], v2 offset:320
	ds_read_b128 v[90:93], v5 offset:256
	ds_read_b128 v[94:97], v5 offset:320
	s_waitcnt lgkmcnt(8)
	v_mfma_f32_16x16x32_f16 v[54:57], v[70:73], v[66:69], v[54:57]
	ds_read_b128 v[66:69], v2 offset:384
	ds_read_b128 v[70:73], v2 offset:448
	ds_read_b128 v[98:101], v5 offset:384
	ds_read_b128 v[102:105], v5 offset:448
	s_waitcnt lgkmcnt(0)
	s_barrier
	s_waitcnt vmcnt(17)
	ds_write_b128 v4, v[136:139]
	s_waitcnt vmcnt(16)
	ds_write_b128 v6, v[140:143]
	s_waitcnt vmcnt(15)
	ds_write_b128 v8, v[144:147]
	s_waitcnt vmcnt(14)
	ds_write_b128 v10, v[148:151]
	s_waitcnt vmcnt(13)
	ds_write_b128 v12, v[152:155]
	s_waitcnt vmcnt(12)
	ds_write_b128 v14, v[156:159]
	s_waitcnt lgkmcnt(0)
	s_barrier
	global_load_dwordx4 v[136:139], v[128:129], off offset:512
	global_load_dwordx4 v[140:143], v[130:131], off offset:512
	global_load_dwordx4 v[144:147], v[132:133], off offset:512
	global_load_dwordx4 v[148:151], v[106:107], off offset:512
	global_load_dwordx4 v[152:155], v[108:109], off offset:512
	global_load_dwordx4 v[156:159], v[110:111], off offset:512
	v_mfma_f32_16x16x32_f16 v[54:57], v[82:85], v[74:77], v[54:57]
	v_mfma_f32_16x16x32_f16 v[54:57], v[86:89], v[78:81], v[54:57]
	v_add_co_u32_e32 v78, vcc, s24, v18
	v_mfma_f32_16x16x32_f16 v[54:57], v[90:93], v[58:61], v[54:57]
	s_nop 0
	v_addc_co_u32_e32 v79, vcc, 0, v19, vcc
	v_add_co_u32_e32 v80, vcc, s24, v26
	v_mfma_f32_16x16x32_f16 v[54:57], v[94:97], v[62:65], v[54:57]
	s_nop 0
	v_addc_co_u32_e32 v81, vcc, 0, v27, vcc
	v_add_co_u32_e32 v82, vcc, s24, v24
	v_mfma_f32_16x16x32_f16 v[54:57], v[98:101], v[66:69], v[54:57]
	s_nop 0
	v_addc_co_u32_e32 v83, vcc, 0, v25, vcc
	ds_read_b128 v[24:27], v5
	v_mfma_f32_16x16x32_f16 v[54:57], v[102:105], v[70:73], v[54:57]
	ds_read_b128 v[58:61], v2
	ds_read_b128 v[62:65], v5 offset:64
	v_add_co_u32_e32 v84, vcc, s24, v22
	ds_read_b128 v[66:69], v2 offset:64
	s_nop 0
	v_addc_co_u32_e32 v85, vcc, 0, v23, vcc
	s_waitcnt lgkmcnt(2)
	v_mfma_f32_16x16x32_f16 v[22:25], v[24:27], v[58:61], v[54:57]
	s_nop 2
	ds_read_b128 v[54:57], v5 offset:128
	ds_read_b128 v[58:61], v2 offset:128
	ds_read_b128 v[70:73], v5 offset:192
	v_add_co_u32_e32 v86, vcc, s24, v20
	s_waitcnt lgkmcnt(3)
	v_mfma_f32_16x16x32_f16 v[22:25], v[62:65], v[66:69], v[22:25]
	v_addc_co_u32_e32 v87, vcc, 0, v21, vcc
	ds_read_b128 v[18:21], v2 offset:192
	s_waitcnt lgkmcnt(2)
	v_mfma_f32_16x16x32_f16 v[22:25], v[54:57], v[58:61], v[22:25]
	ds_read_b128 v[54:57], v2 offset:256
	ds_read_b128 v[58:61], v5 offset:256
	ds_read_b128 v[62:65], v5 offset:320
	v_add_co_u32_e32 v88, vcc, s24, v16
	s_waitcnt lgkmcnt(3)
	v_mfma_f32_16x16x32_f16 v[18:21], v[70:73], v[18:21], v[22:25]
	v_addc_co_u32_e32 v89, vcc, 0, v17, vcc
	s_nop 1
	ds_read_b128 v[22:25], v2 offset:320
	ds_read_b128 v[66:69], v5 offset:384
	s_waitcnt lgkmcnt(3)
	v_mfma_f32_16x16x32_f16 v[16:19], v[58:61], v[54:57], v[18:21]
	ds_read_b128 v[54:57], v2 offset:384
	ds_read_b128 v[58:61], v2 offset:448
	ds_read_b128 v[70:73], v5 offset:448
	s_waitcnt lgkmcnt(0)
	s_barrier
	v_mfma_f32_16x16x32_f16 v[16:19], v[62:65], v[22:25], v[16:19]
	s_waitcnt vmcnt(17)
	ds_write_b128 v4, v[178:181]
	s_waitcnt vmcnt(16)
	ds_write_b128 v6, v[182:185]
	s_waitcnt vmcnt(15)
	ds_write_b128 v8, v[186:189]
	s_waitcnt vmcnt(14)
	ds_write_b128 v10, v[190:193]
	s_waitcnt vmcnt(13)
	ds_write_b128 v12, v[194:197]
	s_waitcnt vmcnt(12)
	ds_write_b128 v14, v[198:201]
	s_waitcnt lgkmcnt(0)
	s_barrier
	global_load_dwordx4 v[178:181], v[128:129], off offset:1024
	global_load_dwordx4 v[182:185], v[130:131], off offset:1024
	global_load_dwordx4 v[186:189], v[132:133], off offset:1024
	global_load_dwordx4 v[190:193], v[106:107], off offset:1024
	global_load_dwordx4 v[194:197], v[108:109], off offset:1024
	global_load_dwordx4 v[198:201], v[110:111], off offset:1024
	ds_read_b128 v[46:49], v5
	v_mfma_f32_16x16x32_f16 v[16:19], v[66:69], v[54:57], v[16:19]
	v_cmp_gt_u32_e32 vcc, 16, v28
	v_mfma_f32_16x16x32_f16 v[16:19], v[70:73], v[58:61], v[16:19]
	ds_read_b128 v[50:53], v5 offset:64
	ds_read_b128 v[54:57], v2
	ds_read_b128 v[58:61], v2 offset:64
	s_waitcnt lgkmcnt(1)
	v_mfma_f32_16x16x32_f16 v[16:19], v[46:49], v[54:57], v[16:19]
	ds_read_b128 v[46:49], v5 offset:128
	ds_read_b128 v[54:57], v5 offset:192
	s_waitcnt lgkmcnt(2)
	v_mfma_f32_16x16x32_f16 v[16:19], v[50:53], v[58:61], v[16:19]
	ds_read_b128 v[50:53], v2 offset:128
	ds_read_b128 v[58:61], v2 offset:192
	s_waitcnt lgkmcnt(1)
	v_mfma_f32_16x16x32_f16 v[16:19], v[46:49], v[50:53], v[16:19]
	ds_read_b128 v[46:49], v5 offset:256
	ds_read_b128 v[50:53], v5 offset:320
	s_waitcnt lgkmcnt(2)
	v_mfma_f32_16x16x32_f16 v[16:19], v[54:57], v[58:61], v[16:19]
	ds_read_b128 v[54:57], v2 offset:256
	ds_read_b128 v[58:61], v2 offset:320
	ds_read_b128 v[62:65], v5 offset:384
	s_waitcnt lgkmcnt(2)
	v_mfma_f32_16x16x32_f16 v[16:19], v[46:49], v[54:57], v[16:19]
	ds_read_b128 v[46:49], v2 offset:384
	ds_read_b128 v[54:57], v2 offset:448
	ds_read_b128 v[66:69], v5 offset:448
	s_waitcnt lgkmcnt(0)
	s_barrier
	s_waitcnt vmcnt(17)
	ds_write_b128 v4, v[206:209]
	s_waitcnt vmcnt(16)
	ds_write_b128 v6, v[210:213]
	s_waitcnt vmcnt(15)
	ds_write_b128 v8, v[214:217]
	s_waitcnt vmcnt(14)
	ds_write_b128 v10, v[218:221]
	s_waitcnt vmcnt(13)
	ds_write_b128 v12, v[120:123]
	s_waitcnt vmcnt(12)
	ds_write_b128 v14, v[124:127]
	s_waitcnt lgkmcnt(0)
	s_barrier
	v_mfma_f32_16x16x32_f16 v[16:19], v[50:53], v[58:61], v[16:19]
	v_mfma_f32_16x16x32_f16 v[16:19], v[62:65], v[46:49], v[16:19]
	ds_read_b128 v[46:49], v5
	v_mfma_f32_16x16x32_f16 v[16:19], v[66:69], v[54:57], v[16:19]
	ds_read_b128 v[50:53], v5 offset:64
	ds_read_b128 v[54:57], v2
	ds_read_b128 v[58:61], v2 offset:64
	s_waitcnt lgkmcnt(1)
	v_mfma_f32_16x16x32_f16 v[16:19], v[46:49], v[54:57], v[16:19]
	ds_read_b128 v[46:49], v5 offset:128
	ds_read_b128 v[54:57], v5 offset:192
	s_waitcnt lgkmcnt(2)
	v_mfma_f32_16x16x32_f16 v[16:19], v[50:53], v[58:61], v[16:19]
	ds_read_b128 v[50:53], v2 offset:128
	ds_read_b128 v[58:61], v2 offset:192
	ds_read_b128 v[62:65], v5 offset:256
	s_waitcnt lgkmcnt(2)
	v_mfma_f32_16x16x32_f16 v[16:19], v[46:49], v[50:53], v[16:19]
	ds_read_b128 v[46:49], v2 offset:256
	ds_read_b128 v[50:53], v2 offset:320
	ds_read_b128 v[66:69], v5 offset:320
	s_waitcnt lgkmcnt(4)
	v_mfma_f32_16x16x32_f16 v[16:19], v[54:57], v[58:61], v[16:19]
	ds_read_b128 v[54:57], v2 offset:384
	ds_read_b128 v[58:61], v2 offset:448
	ds_read_b128 v[70:73], v5 offset:384
	ds_read_b128 v[74:77], v5 offset:448
	s_waitcnt lgkmcnt(0)
	s_barrier
	s_waitcnt vmcnt(11)
	ds_write_b128 v4, v[136:139]
	s_waitcnt vmcnt(10)
	ds_write_b128 v6, v[140:143]
	s_waitcnt vmcnt(9)
	ds_write_b128 v8, v[144:147]
	s_waitcnt vmcnt(8)
	ds_write_b128 v10, v[148:151]
	s_waitcnt vmcnt(7)
	ds_write_b128 v12, v[152:155]
	s_waitcnt vmcnt(6)
	ds_write_b128 v14, v[156:159]
	s_waitcnt lgkmcnt(0)
	s_barrier
	v_mfma_f32_16x16x32_f16 v[16:19], v[62:65], v[46:49], v[16:19]
	ds_read_b128 v[46:49], v5
	v_mfma_f32_16x16x32_f16 v[16:19], v[66:69], v[50:53], v[16:19]
	v_mfma_f32_16x16x32_f16 v[16:19], v[70:73], v[54:57], v[16:19]
	ds_read_b128 v[50:53], v2
	ds_read_b128 v[54:57], v5 offset:64
	v_mfma_f32_16x16x32_f16 v[16:19], v[74:77], v[58:61], v[16:19]
	ds_read_b128 v[58:61], v2 offset:64
	ds_read_b128 v[62:65], v5 offset:128
	s_waitcnt lgkmcnt(3)
	v_mfma_f32_16x16x32_f16 v[16:19], v[46:49], v[50:53], v[16:19]
	ds_read_b128 v[46:49], v2 offset:128
	ds_read_b128 v[50:53], v5 offset:192
	s_waitcnt lgkmcnt(3)
	v_mfma_f32_16x16x32_f16 v[16:19], v[54:57], v[58:61], v[16:19]
	ds_read_b128 v[54:57], v2 offset:192
	ds_read_b128 v[58:61], v5 offset:256
	s_waitcnt lgkmcnt(3)
	v_mfma_f32_16x16x32_f16 v[16:19], v[62:65], v[46:49], v[16:19]
	ds_read_b128 v[46:49], v2 offset:256
	ds_read_b128 v[62:65], v2 offset:320
	ds_read_b128 v[66:69], v5 offset:320
	s_waitcnt lgkmcnt(4)
	v_mfma_f32_16x16x32_f16 v[16:19], v[50:53], v[54:57], v[16:19]
	ds_read_b128 v[50:53], v2 offset:384
	ds_read_b128 v[54:57], v2 offset:448
	ds_read_b128 v[70:73], v5 offset:384
	ds_read_b128 v[74:77], v5 offset:448
	s_waitcnt lgkmcnt(0)
	s_barrier
	v_mfma_f32_16x16x32_f16 v[16:19], v[58:61], v[46:49], v[16:19]
	s_waitcnt vmcnt(5)
	ds_write_b128 v4, v[178:181]
	s_waitcnt vmcnt(4)
	ds_write_b128 v6, v[182:185]
	s_waitcnt vmcnt(3)
	ds_write_b128 v8, v[186:189]
	s_waitcnt vmcnt(2)
	ds_write_b128 v10, v[190:193]
	s_waitcnt vmcnt(1)
	ds_write_b128 v12, v[194:197]
	s_waitcnt vmcnt(0)
	ds_write_b128 v14, v[198:201]
	v_mfma_f32_16x16x32_f16 v[16:19], v[66:69], v[62:65], v[16:19]
	s_waitcnt lgkmcnt(0)
	s_barrier
	v_add_u32_e32 v234, s15, v3
	v_ashrrev_i32_e32 v235, 31, v234
	v_lshlrev_b64 v[236:237], 10, v[0:1]
	v_lshl_add_u64 v[236:237], v[236:237], 0, v[234:235]
	v_lshl_add_u64 v[238:239], v[236:237], 2, s[38:39]
	v_lshl_add_u64 v[238:239], s[100:101], 0, v[238:239]
	v_lshlrev_b64 v[234:235], 2, v[234:235]
	global_load_dwordx4 v[226:229], v[238:239], off
	v_lshl_add_u64 v[238:239], s[2:3], 0, v[234:235]
	global_load_dwordx4 v[222:225], v[238:239], off
	v_lshl_add_u64 v[238:239], s[4:5], 0, v[234:235]
	global_load_dwordx4 v[230:233], v[238:239], off
	ds_read_b128 v[6:9], v5
	v_mfma_f32_16x16x32_f16 v[10:13], v[70:73], v[50:53], v[16:19]
	s_nop 3
	ds_read_b128 v[14:17], v2
	ds_read_b128 v[18:21], v5 offset:64
	ds_read_b128 v[22:25], v2 offset:64
	ds_read_b128 v[30:33], v5 offset:128
	v_add_u32_e32 v26, s15, v3
	v_mfma_f32_16x16x32_f16 v[10:13], v[74:77], v[54:57], v[10:13]
	v_lshlrev_b64 v[34:35], 10, v[0:1]
	v_ashrrev_i32_e32 v27, 31, v26
	v_lshl_add_u64 v[34:35], v[34:35], 0, v[26:27]
	s_waitcnt lgkmcnt(3)
	v_mfma_f32_16x16x32_f16 v[6:9], v[6:9], v[14:17], v[10:13]
	s_nop 2
	ds_read_b128 v[10:13], v2 offset:128
	ds_read_b128 v[14:17], v5 offset:192
	v_lshlrev_b64 v[26:27], 2, v[26:27]
	v_lshl_add_u64 v[36:37], v[34:35], 2, s[38:39]
	s_waitcnt lgkmcnt(3)
	v_mfma_f32_16x16x32_f16 v[6:9], v[18:21], v[22:25], v[6:9]
	ds_read_b128 v[18:21], v2 offset:192
	ds_read_b128 v[22:25], v5 offset:256
	s_waitcnt lgkmcnt(3)
	v_mfma_f32_16x16x32_f16 v[6:9], v[30:33], v[10:13], v[6:9]
	ds_read_b128 v[10:13], v2 offset:256
	ds_read_b128 v[30:33], v5 offset:320
	s_waitcnt lgkmcnt(3)
	v_mfma_f32_16x16x32_f16 v[6:9], v[14:17], v[18:21], v[6:9]
	ds_read_b128 v[14:17], v2 offset:320
	ds_read_b128 v[18:21], v5 offset:384
	s_waitcnt lgkmcnt(3)
	v_mfma_f32_16x16x32_f16 v[6:9], v[22:25], v[10:13], v[6:9]
	ds_read_b128 v[10:13], v2 offset:384
	v_lshl_add_u64 v[22:23], s[2:3], 0, v[26:27]
	s_waitcnt lgkmcnt(2)
	v_mfma_f32_16x16x32_f16 v[6:9], v[30:33], v[14:17], v[6:9]
	ds_read_b128 v[14:17], v2 offset:448
	ds_read_b128 v[2:5], v5 offset:448
	s_nop 0
	s_waitcnt lgkmcnt(2)
	v_mfma_f32_16x16x32_f16 v[6:9], v[18:21], v[10:13], v[6:9]
	s_nop 0
	s_nop 0
	v_lshl_add_u64 v[18:19], s[4:5], 0, v[26:27]
	s_waitcnt lgkmcnt(0)
	v_mfma_f32_16x16x32_f16 v[2:5], v[2:5], v[14:17], v[6:9]
	s_waitcnt vmcnt(0)
	s_nop 2
	v_pk_mul_f32 v[6:7], v[224:225], 0.5 op_sel_hi:[1,0]
	v_pk_mul_f32 v[8:9], v[222:223], 0.5 op_sel_hi:[1,0]
	s_waitcnt vmcnt(0)
	s_nop 0
	v_pk_fma_f32 v[6:7], v[4:5], v[6:7], v[228:229]
	v_pk_fma_f32 v[4:5], v[2:3], v[8:9], v[226:227]
	global_store_dwordx4 v[36:37], v[4:7], off
	s_nop 0
	v_mul_f32_e32 v2, v5, v5
	v_mul_f32_e32 v3, v7, v7
	v_fmac_f32_e32 v2, v4, v4
	v_fmac_f32_e32 v3, v6, v6
	v_add_f32_e32 v2, v2, v3
	ds_bpermute_b32 v3, v134, v2
	v_lshl_add_u64 v[12:13], v[34:35], 1, s[42:43]
	s_waitcnt lgkmcnt(0)
	v_add_f32_e32 v2, v2, v3
	ds_bpermute_b32 v3, v135, v2
	s_nop 0
	v_pk_mul_f32 v[6:7], v[232:233], v[6:7]
	v_pk_mul_f32 v[4:5], v[230:231], v[4:5]
	s_nop 0
	v_cvt_pk_f16_f32 v4, v4, v5
	v_cvt_pk_f16_f32 v5, v6, v7
	global_store_dwordx2 v[12:13], v[4:5], off
	s_and_saveexec_b64 s[14:15], vcc
	s_cbranch_execz .LBB0_364
	v_lshlrev_b32_e32 v0, 2, v0
	s_waitcnt lgkmcnt(0)
	v_add_f32_e32 v2, v2, v3
	global_atomic_add_f32 v0, v2, s[12:13]
	s_branch .LBB0_364

.LBB0_1018:
	v_mov_b32_e32 v28, v176
	s_and_b32 s14, s21, 0x1e0
	v_add_u32_e32 v8, s1, v28
	s_and_b32 s15, s19, 0xffffffc0
	s_bitset1_b32 s14, 14
	s_sub_i32 s26, s15, 32
	v_lshlrev_b32_e32 v0, 4, v28
	v_ashrrev_i32_e32 v9, 5, v8
	v_and_b32_e32 v0, 0x1f0, v0
	v_mov_b32_e32 v10, s26
	v_mov_b32_e32 v11, s14
	v_cmp_gt_i32_e32 vcc, 32, v9
	v_lshl_add_u64 v[2:3], s[10:11], 0, v[0:1]
	v_lshl_add_u64 v[4:5], s[36:37], 0, v[0:1]
	v_cndmask_b32_e32 v6, v10, v11, vcc
	v_add_u32_e32 v12, v6, v9
	v_cndmask_b32_e32 v7, v3, v5, vcc
	v_cndmask_b32_e32 v6, v2, v4, vcc
	v_mad_i64_i32 v[18:19], s[26:27], v12, s22, v[6:7]
	v_add_u32_e32 v6, 0x200, v8
	v_ashrrev_i32_e32 v12, 5, v6
	v_cmp_gt_i32_e32 vcc, 32, v12
	v_add_u32_e32 v0, 0, v0
	s_or_b32 s15, s15, s17
	v_cndmask_b32_e32 v6, v10, v11, vcc
	v_add_u32_e32 v13, v6, v12
	v_cndmask_b32_e32 v7, v3, v5, vcc
	v_cndmask_b32_e32 v6, v2, v4, vcc
	v_mad_i64_i32 v[16:17], s[26:27], v13, s22, v[6:7]
	v_add_u32_e32 v6, 0x400, v8
	v_ashrrev_i32_e32 v13, 5, v6
	v_cmp_gt_i32_e32 vcc, 32, v13
	s_add_i32 s14, s14, s16
	s_nop 0
	v_cndmask_b32_e32 v6, v10, v11, vcc
	v_add_u32_e32 v14, v6, v13
	v_cndmask_b32_e32 v7, v3, v5, vcc
	v_cndmask_b32_e32 v6, v2, v4, vcc
	v_mad_i64_i32 v[20:21], s[26:27], v14, s22, v[6:7]
	v_add_u32_e32 v6, 0x600, v8
	v_ashrrev_i32_e32 v14, 5, v6
	v_cmp_gt_i32_e32 vcc, 32, v14
	s_nop 1
	v_cndmask_b32_e32 v6, v10, v11, vcc
	v_add_u32_e32 v15, v6, v14
	v_cndmask_b32_e32 v7, v3, v5, vcc
	v_cndmask_b32_e32 v6, v2, v4, vcc
	v_mad_i64_i32 v[22:23], s[26:27], v15, s22, v[6:7]
	v_add_u32_e32 v6, 0x800, v8
	v_ashrrev_i32_e32 v15, 5, v6
	v_cmp_gt_i32_e32 vcc, 32, v15
	s_nop 1
	v_cndmask_b32_e32 v6, v10, v11, vcc
	v_add_u32_e32 v24, v6, v15
	v_cndmask_b32_e32 v7, v3, v5, vcc
	v_cndmask_b32_e32 v6, v2, v4, vcc
	v_mad_i64_i32 v[24:25], s[26:27], v24, s22, v[6:7]
	v_add_u32_e32 v6, 0xa00, v8
	v_ashrrev_i32_e32 v29, 5, v6
	v_cmp_gt_i32_e32 vcc, 32, v29
	s_nop 1
	v_cndmask_b32_e32 v6, v10, v11, vcc
	v_add_u32_e32 v6, v6, v29
	v_cndmask_b32_e32 v3, v3, v5, vcc
	v_cndmask_b32_e32 v2, v2, v4, vcc
	v_mad_i64_i32 v[26:27], s[26:27], v6, s22, v[2:3]
	global_load_dwordx4 v[136:139], v[18:19], off
	global_load_dwordx4 v[140:143], v[16:17], off
	global_load_dwordx4 v[144:147], v[20:21], off
	global_load_dwordx4 v[148:151], v[22:23], off
	global_load_dwordx4 v[152:155], v[24:25], off
	global_load_dwordx4 v[156:159], v[26:27], off
	global_load_dwordx4 v[178:181], v[18:19], off offset:512
	global_load_dwordx4 v[182:185], v[16:17], off offset:512
	global_load_dwordx4 v[186:189], v[20:21], off offset:512
	global_load_dwordx4 v[190:193], v[22:23], off offset:512
	global_load_dwordx4 v[194:197], v[24:25], off offset:512
	global_load_dwordx4 v[198:201], v[26:27], off offset:512
	global_load_dwordx4 v[206:209], v[18:19], off offset:1024
	global_load_dwordx4 v[210:213], v[16:17], off offset:1024
	global_load_dwordx4 v[214:217], v[20:21], off offset:1024
	global_load_dwordx4 v[218:221], v[22:23], off offset:1024
	global_load_dwordx4 v[120:123], v[24:25], off offset:1024
	global_load_dwordx4 v[124:127], v[26:27], off offset:1024
	v_mov_b32_e32 v112, 0x1000
	v_mov_b32_e32 v113, 0
	v_lshl_add_u64 v[128:129], v[18:19], 0, v[112:113]
	v_lshl_add_u64 v[130:131], v[16:17], 0, v[112:113]
	v_lshl_add_u64 v[132:133], v[20:21], 0, v[112:113]
	v_lshl_add_u64 v[106:107], v[22:23], 0, v[112:113]
	v_lshl_add_u64 v[108:109], v[24:25], 0, v[112:113]
	v_lshl_add_u64 v[110:111], v[26:27], 0, v[112:113]
	v_mad_u64_u32 v[4:5], s[26:27], v9, s23, v[0:1]
	v_mad_u64_u32 v[6:7], s[26:27], v12, s23, v[0:1]
	v_mad_u64_u32 v[8:9], s[26:27], v13, s23, v[0:1]
	v_mad_u64_u32 v[10:11], s[26:27], v14, s23, v[0:1]
	v_mad_u64_u32 v[12:13], s[26:27], v15, s23, v[0:1]
	v_mad_u64_u32 v[14:15], s[26:27], v29, s23, v[0:1]
	s_barrier
	v_and_b32_e32 v0, 15, v28
	v_and_b32_e32 v2, -16, v28
	v_add_u32_e32 v2, 0, v2
	v_or_b32_e32 v5, s18, v0
	v_mad_u32_u24 v5, v5, s23, v2
	v_or_b32_e32 v3, s16, v0
	v_mad_u64_u32 v[2:3], s[26:27], v3, s23, v[2:3]
	v_ashrrev_i32_e32 v3, 2, v28
	v_and_b32_e32 v3, -4, v3
	v_or_b32_e32 v0, s14, v0
	s_waitcnt vmcnt(17)
	ds_write_b128 v4, v[136:139]
	s_waitcnt vmcnt(16)
	ds_write_b128 v6, v[140:143]
	s_waitcnt vmcnt(15)
	ds_write_b128 v8, v[144:147]
	s_waitcnt vmcnt(14)
	ds_write_b128 v10, v[148:151]
	s_waitcnt vmcnt(13)
	ds_write_b128 v12, v[152:155]
	s_waitcnt vmcnt(12)
	ds_write_b128 v14, v[156:159]
	s_waitcnt lgkmcnt(0)
	s_barrier
	global_load_dwordx4 v[136:139], v[18:19], off offset:1536
	global_load_dwordx4 v[140:143], v[16:17], off offset:1536
	global_load_dwordx4 v[144:147], v[20:21], off offset:1536
	global_load_dwordx4 v[148:151], v[22:23], off offset:1536
	global_load_dwordx4 v[152:155], v[24:25], off offset:1536
	global_load_dwordx4 v[156:159], v[26:27], off offset:1536
	ds_read_b128 v[54:57], v5
	ds_read_b128 v[58:61], v5 offset:64
	ds_read_b128 v[62:65], v2
	ds_read_b128 v[66:69], v2 offset:64
	s_waitcnt lgkmcnt(1)
	v_mfma_f32_16x16x32_f16 v[54:57], v[54:57], v[62:65], 0
	ds_read_b128 v[62:65], v5 offset:128
	ds_read_b128 v[70:73], v5 offset:192
	s_waitcnt lgkmcnt(2)
	v_mfma_f32_16x16x32_f16 v[54:57], v[58:61], v[66:69], v[54:57]
	ds_read_b128 v[58:61], v2 offset:128
	ds_read_b128 v[66:69], v2 offset:192
	s_waitcnt lgkmcnt(1)
	v_mfma_f32_16x16x32_f16 v[54:57], v[62:65], v[58:61], v[54:57]
	ds_read_b128 v[58:61], v5 offset:256
	ds_read_b128 v[62:65], v5 offset:320
	s_waitcnt lgkmcnt(2)
	v_mfma_f32_16x16x32_f16 v[54:57], v[70:73], v[66:69], v[54:57]
	ds_read_b128 v[66:69], v2 offset:256
	ds_read_b128 v[70:73], v2 offset:320
	ds_read_b128 v[74:77], v5 offset:384
	s_waitcnt lgkmcnt(2)
	v_mfma_f32_16x16x32_f16 v[54:57], v[58:61], v[66:69], v[54:57]
	ds_read_b128 v[58:61], v2 offset:384
	ds_read_b128 v[66:69], v2 offset:448
	ds_read_b128 v[78:81], v5 offset:448
	s_waitcnt lgkmcnt(0)
	s_barrier
	s_waitcnt vmcnt(17)
	ds_write_b128 v4, v[178:181]
	s_waitcnt vmcnt(16)
	ds_write_b128 v6, v[182:185]
	s_waitcnt vmcnt(15)
	ds_write_b128 v8, v[186:189]
	s_waitcnt vmcnt(14)
	ds_write_b128 v10, v[190:193]
	s_waitcnt vmcnt(13)
	ds_write_b128 v12, v[194:197]
	s_waitcnt vmcnt(12)
	ds_write_b128 v14, v[198:201]
	s_waitcnt lgkmcnt(0)
	s_barrier
	global_load_dwordx4 v[178:181], v[18:19], off offset:2048
	global_load_dwordx4 v[182:185], v[16:17], off offset:2048
	global_load_dwordx4 v[186:189], v[20:21], off offset:2048
	global_load_dwordx4 v[190:193], v[22:23], off offset:2048
	global_load_dwordx4 v[194:197], v[24:25], off offset:2048
	global_load_dwordx4 v[198:201], v[26:27], off offset:2048
	v_mfma_f32_16x16x32_f16 v[54:57], v[62:65], v[70:73], v[54:57]
	v_mfma_f32_16x16x32_f16 v[54:57], v[74:77], v[58:61], v[54:57]
	ds_read_b128 v[58:61], v5
	v_mfma_f32_16x16x32_f16 v[54:57], v[78:81], v[66:69], v[54:57]
	ds_read_b128 v[62:65], v5 offset:64
	ds_read_b128 v[66:69], v2
	ds_read_b128 v[70:73], v2 offset:64
	s_waitcnt lgkmcnt(1)
	v_mfma_f32_16x16x32_f16 v[54:57], v[58:61], v[66:69], v[54:57]
	ds_read_b128 v[58:61], v5 offset:128
	ds_read_b128 v[66:69], v5 offset:192
	s_waitcnt lgkmcnt(2)
	v_mfma_f32_16x16x32_f16 v[54:57], v[62:65], v[70:73], v[54:57]
	ds_read_b128 v[62:65], v2 offset:128
	ds_read_b128 v[70:73], v2 offset:192
	s_waitcnt lgkmcnt(1)
	v_mfma_f32_16x16x32_f16 v[54:57], v[58:61], v[62:65], v[54:57]
	ds_read_b128 v[58:61], v5 offset:256
	ds_read_b128 v[62:65], v5 offset:320
	s_waitcnt lgkmcnt(2)
	v_mfma_f32_16x16x32_f16 v[54:57], v[66:69], v[70:73], v[54:57]
	ds_read_b128 v[66:69], v2 offset:256
	ds_read_b128 v[70:73], v2 offset:320
	ds_read_b128 v[74:77], v5 offset:384
	s_waitcnt lgkmcnt(2)
	v_mfma_f32_16x16x32_f16 v[54:57], v[58:61], v[66:69], v[54:57]
	ds_read_b128 v[58:61], v2 offset:384
	ds_read_b128 v[66:69], v2 offset:448
	ds_read_b128 v[78:81], v5 offset:448
	s_waitcnt lgkmcnt(0)
	s_barrier
	s_waitcnt vmcnt(17)
	ds_write_b128 v4, v[206:209]
	s_waitcnt vmcnt(16)
	ds_write_b128 v6, v[210:213]
	s_waitcnt vmcnt(15)
	ds_write_b128 v8, v[214:217]
	s_waitcnt vmcnt(14)
	ds_write_b128 v10, v[218:221]
	s_waitcnt vmcnt(13)
	ds_write_b128 v12, v[120:123]
	s_waitcnt vmcnt(12)
	ds_write_b128 v14, v[124:127]
	s_waitcnt lgkmcnt(0)
	s_barrier
	global_load_dwordx4 v[206:209], v[18:19], off offset:2560
	global_load_dwordx4 v[210:213], v[16:17], off offset:2560
	global_load_dwordx4 v[214:217], v[20:21], off offset:2560
	global_load_dwordx4 v[218:221], v[22:23], off offset:2560
	global_load_dwordx4 v[120:123], v[24:25], off offset:2560
	global_load_dwordx4 v[124:127], v[26:27], off offset:2560
	v_mfma_f32_16x16x32_f16 v[54:57], v[62:65], v[70:73], v[54:57]
	v_mfma_f32_16x16x32_f16 v[54:57], v[74:77], v[58:61], v[54:57]
	ds_read_b128 v[58:61], v5
	v_mfma_f32_16x16x32_f16 v[54:57], v[78:81], v[66:69], v[54:57]
	ds_read_b128 v[62:65], v5 offset:64
	ds_read_b128 v[66:69], v2
	ds_read_b128 v[70:73], v2 offset:64
	s_waitcnt lgkmcnt(1)
	v_mfma_f32_16x16x32_f16 v[54:57], v[58:61], v[66:69], v[54:57]
	ds_read_b128 v[58:61], v5 offset:128
	ds_read_b128 v[66:69], v5 offset:192
	s_waitcnt lgkmcnt(2)
	v_mfma_f32_16x16x32_f16 v[54:57], v[62:65], v[70:73], v[54:57]
	ds_read_b128 v[62:65], v2 offset:128
	ds_read_b128 v[70:73], v2 offset:192
	s_waitcnt lgkmcnt(1)
	v_mfma_f32_16x16x32_f16 v[54:57], v[58:61], v[62:65], v[54:57]
	ds_read_b128 v[58:61], v5 offset:256
	ds_read_b128 v[62:65], v5 offset:320
	s_waitcnt lgkmcnt(2)
	v_mfma_f32_16x16x32_f16 v[54:57], v[66:69], v[70:73], v[54:57]
	ds_read_b128 v[66:69], v2 offset:256
	ds_read_b128 v[70:73], v2 offset:320
	ds_read_b128 v[74:77], v5 offset:384
	s_waitcnt lgkmcnt(2)
	v_mfma_f32_16x16x32_f16 v[54:57], v[58:61], v[66:69], v[54:57]
	ds_read_b128 v[58:61], v2 offset:384
	ds_read_b128 v[66:69], v2 offset:448
	ds_read_b128 v[78:81], v5 offset:448
	s_waitcnt lgkmcnt(0)
	s_barrier
	s_waitcnt vmcnt(17)
	ds_write_b128 v4, v[136:139]
	s_waitcnt vmcnt(16)
	ds_write_b128 v6, v[140:143]
	s_waitcnt vmcnt(15)
	ds_write_b128 v8, v[144:147]
	s_waitcnt vmcnt(14)
	ds_write_b128 v10, v[148:151]
	s_waitcnt vmcnt(13)
	ds_write_b128 v12, v[152:155]
	s_waitcnt vmcnt(12)
	ds_write_b128 v14, v[156:159]
	s_waitcnt lgkmcnt(0)
	s_barrier
	global_load_dwordx4 v[136:139], v[18:19], off offset:3072
	global_load_dwordx4 v[140:143], v[16:17], off offset:3072
	global_load_dwordx4 v[144:147], v[20:21], off offset:3072
	global_load_dwordx4 v[148:151], v[22:23], off offset:3072
	global_load_dwordx4 v[152:155], v[24:25], off offset:3072
	global_load_dwordx4 v[156:159], v[26:27], off offset:3072
	v_mfma_f32_16x16x32_f16 v[54:57], v[62:65], v[70:73], v[54:57]
	v_mfma_f32_16x16x32_f16 v[54:57], v[74:77], v[58:61], v[54:57]
	ds_read_b128 v[58:61], v5
	v_mfma_f32_16x16x32_f16 v[54:57], v[78:81], v[66:69], v[54:57]
	ds_read_b128 v[62:65], v5 offset:64
	ds_read_b128 v[66:69], v2
	ds_read_b128 v[70:73], v2 offset:64
	s_waitcnt lgkmcnt(1)
	v_mfma_f32_16x16x32_f16 v[54:57], v[58:61], v[66:69], v[54:57]
	ds_read_b128 v[58:61], v5 offset:128
	ds_read_b128 v[66:69], v5 offset:192
	s_waitcnt lgkmcnt(2)
	v_mfma_f32_16x16x32_f16 v[54:57], v[62:65], v[70:73], v[54:57]
	ds_read_b128 v[62:65], v2 offset:128
	ds_read_b128 v[70:73], v2 offset:192
	s_waitcnt lgkmcnt(1)
	v_mfma_f32_16x16x32_f16 v[54:57], v[58:61], v[62:65], v[54:57]
	ds_read_b128 v[58:61], v5 offset:256
	ds_read_b128 v[62:65], v5 offset:320
	s_waitcnt lgkmcnt(2)
	v_mfma_f32_16x16x32_f16 v[54:57], v[66:69], v[70:73], v[54:57]
	ds_read_b128 v[66:69], v2 offset:256
	ds_read_b128 v[70:73], v2 offset:320
	ds_read_b128 v[74:77], v5 offset:384
	s_waitcnt lgkmcnt(2)
	v_mfma_f32_16x16x32_f16 v[54:57], v[58:61], v[66:69], v[54:57]
	ds_read_b128 v[58:61], v2 offset:384
	ds_read_b128 v[66:69], v2 offset:448
	ds_read_b128 v[78:81], v5 offset:448
	s_waitcnt lgkmcnt(0)
	s_barrier
	s_waitcnt vmcnt(17)
	ds_write_b128 v4, v[178:181]
	s_waitcnt vmcnt(16)
	ds_write_b128 v6, v[182:185]
	s_waitcnt vmcnt(15)
	ds_write_b128 v8, v[186:189]
	s_waitcnt vmcnt(14)
	ds_write_b128 v10, v[190:193]
	s_waitcnt vmcnt(13)
	ds_write_b128 v12, v[194:197]
	s_waitcnt vmcnt(12)
	ds_write_b128 v14, v[198:201]
	s_waitcnt lgkmcnt(0)
	s_barrier
	global_load_dwordx4 v[178:181], v[18:19], off offset:3584
	global_load_dwordx4 v[182:185], v[16:17], off offset:3584
	global_load_dwordx4 v[186:189], v[20:21], off offset:3584
	global_load_dwordx4 v[190:193], v[22:23], off offset:3584
	global_load_dwordx4 v[194:197], v[24:25], off offset:3584
	global_load_dwordx4 v[198:201], v[26:27], off offset:3584
	v_mfma_f32_16x16x32_f16 v[54:57], v[62:65], v[70:73], v[54:57]
	v_mfma_f32_16x16x32_f16 v[54:57], v[74:77], v[58:61], v[54:57]
	ds_read_b128 v[58:61], v5
	v_mfma_f32_16x16x32_f16 v[54:57], v[78:81], v[66:69], v[54:57]
	ds_read_b128 v[62:65], v5 offset:64
	ds_read_b128 v[66:69], v2
	ds_read_b128 v[70:73], v2 offset:64
	s_waitcnt lgkmcnt(1)
	v_mfma_f32_16x16x32_f16 v[54:57], v[58:61], v[66:69], v[54:57]
	ds_read_b128 v[58:61], v5 offset:128
	ds_read_b128 v[66:69], v5 offset:192
	s_waitcnt lgkmcnt(2)
	v_mfma_f32_16x16x32_f16 v[54:57], v[62:65], v[70:73], v[54:57]
	ds_read_b128 v[62:65], v2 offset:128
	ds_read_b128 v[70:73], v2 offset:192
	s_waitcnt lgkmcnt(1)
	v_mfma_f32_16x16x32_f16 v[54:57], v[58:61], v[62:65], v[54:57]
	ds_read_b128 v[58:61], v5 offset:256
	ds_read_b128 v[62:65], v5 offset:320
	s_waitcnt lgkmcnt(2)
	v_mfma_f32_16x16x32_f16 v[54:57], v[66:69], v[70:73], v[54:57]
	ds_read_b128 v[66:69], v2 offset:256
	ds_read_b128 v[70:73], v2 offset:320
	ds_read_b128 v[74:77], v5 offset:384
	s_waitcnt lgkmcnt(2)
	v_mfma_f32_16x16x32_f16 v[54:57], v[58:61], v[66:69], v[54:57]
	ds_read_b128 v[58:61], v2 offset:384
	ds_read_b128 v[66:69], v2 offset:448
	ds_read_b128 v[78:81], v5 offset:448
	s_waitcnt lgkmcnt(0)
	s_barrier
	s_waitcnt vmcnt(17)
	ds_write_b128 v4, v[206:209]
	s_waitcnt vmcnt(16)
	ds_write_b128 v6, v[210:213]
	s_waitcnt vmcnt(15)
	ds_write_b128 v8, v[214:217]
	s_waitcnt vmcnt(14)
	ds_write_b128 v10, v[218:221]
	s_waitcnt vmcnt(13)
	ds_write_b128 v12, v[120:123]
	s_waitcnt vmcnt(12)
	ds_write_b128 v14, v[124:127]
	s_waitcnt lgkmcnt(0)
	s_barrier
	global_load_dwordx4 v[206:209], v[128:129], off
	global_load_dwordx4 v[210:213], v[130:131], off
	global_load_dwordx4 v[214:217], v[132:133], off
	global_load_dwordx4 v[218:221], v[106:107], off
	global_load_dwordx4 v[120:123], v[108:109], off
	global_load_dwordx4 v[124:127], v[110:111], off
	v_mfma_f32_16x16x32_f16 v[54:57], v[62:65], v[70:73], v[54:57]
	v_mfma_f32_16x16x32_f16 v[54:57], v[74:77], v[58:61], v[54:57]
	ds_read_b128 v[58:61], v5
	v_mfma_f32_16x16x32_f16 v[54:57], v[78:81], v[66:69], v[54:57]
	ds_read_b128 v[62:65], v2
	ds_read_b128 v[66:69], v2 offset:64
	ds_read_b128 v[70:73], v5 offset:64
	ds_read_b128 v[74:77], v2 offset:128
	ds_read_b128 v[78:81], v2 offset:192
	ds_read_b128 v[82:85], v5 offset:128
	ds_read_b128 v[86:89], v5 offset:192
	s_waitcnt lgkmcnt(6)
	v_mfma_f32_16x16x32_f16 v[54:57], v[58:61], v[62:65], v[54:57]
	ds_read_b128 v[58:61], v2 offset:256
	ds_read_b128 v[62:65], v2 offset:320
	ds_read_b128 v[90:93], v5 offset:256
	ds_read_b128 v[94:97], v5 offset:320
	s_waitcnt lgkmcnt(8)
	v_mfma_f32_16x16x32_f16 v[54:57], v[70:73], v[66:69], v[54:57]
	ds_read_b128 v[66:69], v2 offset:384
	ds_read_b128 v[70:73], v2 offset:448
	ds_read_b128 v[98:101], v5 offset:384
	ds_read_b128 v[102:105], v5 offset:448
	s_waitcnt lgkmcnt(0)
	s_barrier
	s_waitcnt vmcnt(17)
	ds_write_b128 v4, v[136:139]
	s_waitcnt vmcnt(16)
	ds_write_b128 v6, v[140:143]
	s_waitcnt vmcnt(15)
	ds_write_b128 v8, v[144:147]
	s_waitcnt vmcnt(14)
	ds_write_b128 v10, v[148:151]
	s_waitcnt vmcnt(13)
	ds_write_b128 v12, v[152:155]
	s_waitcnt vmcnt(12)
	ds_write_b128 v14, v[156:159]
	s_waitcnt lgkmcnt(0)
	s_barrier
	global_load_dwordx4 v[136:139], v[128:129], off offset:512
	global_load_dwordx4 v[140:143], v[130:131], off offset:512
	global_load_dwordx4 v[144:147], v[132:133], off offset:512
	global_load_dwordx4 v[148:151], v[106:107], off offset:512
	global_load_dwordx4 v[152:155], v[108:109], off offset:512
	global_load_dwordx4 v[156:159], v[110:111], off offset:512
	v_mfma_f32_16x16x32_f16 v[54:57], v[82:85], v[74:77], v[54:57]
	v_mfma_f32_16x16x32_f16 v[54:57], v[86:89], v[78:81], v[54:57]
	v_add_co_u32_e32 v78, vcc, s24, v18
	v_mfma_f32_16x16x32_f16 v[54:57], v[90:93], v[58:61], v[54:57]
	s_nop 0
	v_addc_co_u32_e32 v79, vcc, 0, v19, vcc
	v_add_co_u32_e32 v80, vcc, s24, v26
	v_mfma_f32_16x16x32_f16 v[54:57], v[94:97], v[62:65], v[54:57]
	s_nop 0
	v_addc_co_u32_e32 v81, vcc, 0, v27, vcc
	v_add_co_u32_e32 v82, vcc, s24, v24
	v_mfma_f32_16x16x32_f16 v[54:57], v[98:101], v[66:69], v[54:57]
	s_nop 0
	v_addc_co_u32_e32 v83, vcc, 0, v25, vcc
	ds_read_b128 v[24:27], v5
	v_mfma_f32_16x16x32_f16 v[54:57], v[102:105], v[70:73], v[54:57]
	ds_read_b128 v[58:61], v2
	ds_read_b128 v[62:65], v5 offset:64
	v_add_co_u32_e32 v84, vcc, s24, v22
	ds_read_b128 v[66:69], v2 offset:64
	s_nop 0
	v_addc_co_u32_e32 v85, vcc, 0, v23, vcc
	s_waitcnt lgkmcnt(2)
	v_mfma_f32_16x16x32_f16 v[22:25], v[24:27], v[58:61], v[54:57]
	s_nop 2
	ds_read_b128 v[54:57], v5 offset:128
	ds_read_b128 v[58:61], v2 offset:128
	ds_read_b128 v[70:73], v5 offset:192
	v_add_co_u32_e32 v86, vcc, s24, v20
	s_waitcnt lgkmcnt(3)
	v_mfma_f32_16x16x32_f16 v[22:25], v[62:65], v[66:69], v[22:25]
	v_addc_co_u32_e32 v87, vcc, 0, v21, vcc
	ds_read_b128 v[18:21], v2 offset:192
	s_waitcnt lgkmcnt(2)
	v_mfma_f32_16x16x32_f16 v[22:25], v[54:57], v[58:61], v[22:25]
	ds_read_b128 v[54:57], v2 offset:256
	ds_read_b128 v[58:61], v5 offset:256
	ds_read_b128 v[62:65], v5 offset:320
	v_add_co_u32_e32 v88, vcc, s24, v16
	s_waitcnt lgkmcnt(3)
	v_mfma_f32_16x16x32_f16 v[18:21], v[70:73], v[18:21], v[22:25]
	v_addc_co_u32_e32 v89, vcc, 0, v17, vcc
	s_nop 1
	ds_read_b128 v[22:25], v2 offset:320
	ds_read_b128 v[66:69], v5 offset:384
	s_waitcnt lgkmcnt(3)
	v_mfma_f32_16x16x32_f16 v[16:19], v[58:61], v[54:57], v[18:21]
	ds_read_b128 v[54:57], v2 offset:384
	ds_read_b128 v[58:61], v2 offset:448
	ds_read_b128 v[70:73], v5 offset:448
	s_waitcnt lgkmcnt(0)
	s_barrier
	v_mfma_f32_16x16x32_f16 v[16:19], v[62:65], v[22:25], v[16:19]
	s_waitcnt vmcnt(17)
	ds_write_b128 v4, v[178:181]
	s_waitcnt vmcnt(16)
	ds_write_b128 v6, v[182:185]
	s_waitcnt vmcnt(15)
	ds_write_b128 v8, v[186:189]
	s_waitcnt vmcnt(14)
	ds_write_b128 v10, v[190:193]
	s_waitcnt vmcnt(13)
	ds_write_b128 v12, v[194:197]
	s_waitcnt vmcnt(12)
	ds_write_b128 v14, v[198:201]
	s_waitcnt lgkmcnt(0)
	s_barrier
	global_load_dwordx4 v[178:181], v[128:129], off offset:1024
	global_load_dwordx4 v[182:185], v[130:131], off offset:1024
	global_load_dwordx4 v[186:189], v[132:133], off offset:1024
	global_load_dwordx4 v[190:193], v[106:107], off offset:1024
	global_load_dwordx4 v[194:197], v[108:109], off offset:1024
	global_load_dwordx4 v[198:201], v[110:111], off offset:1024
	ds_read_b128 v[46:49], v5
	v_mfma_f32_16x16x32_f16 v[16:19], v[66:69], v[54:57], v[16:19]
	v_cmp_gt_u32_e32 vcc, 16, v28
	v_mfma_f32_16x16x32_f16 v[16:19], v[70:73], v[58:61], v[16:19]
	ds_read_b128 v[50:53], v5 offset:64
	ds_read_b128 v[54:57], v2
	ds_read_b128 v[58:61], v2 offset:64
	s_waitcnt lgkmcnt(1)
	v_mfma_f32_16x16x32_f16 v[16:19], v[46:49], v[54:57], v[16:19]
	ds_read_b128 v[46:49], v5 offset:128
	ds_read_b128 v[54:57], v5 offset:192
	s_waitcnt lgkmcnt(2)
	v_mfma_f32_16x16x32_f16 v[16:19], v[50:53], v[58:61], v[16:19]
	ds_read_b128 v[50:53], v2 offset:128
	ds_read_b128 v[58:61], v2 offset:192
	s_waitcnt lgkmcnt(1)
	v_mfma_f32_16x16x32_f16 v[16:19], v[46:49], v[50:53], v[16:19]
	ds_read_b128 v[46:49], v5 offset:256
	ds_read_b128 v[50:53], v5 offset:320
	s_waitcnt lgkmcnt(2)
	v_mfma_f32_16x16x32_f16 v[16:19], v[54:57], v[58:61], v[16:19]
	ds_read_b128 v[54:57], v2 offset:256
	ds_read_b128 v[58:61], v2 offset:320
	ds_read_b128 v[62:65], v5 offset:384
	s_waitcnt lgkmcnt(2)
	v_mfma_f32_16x16x32_f16 v[16:19], v[46:49], v[54:57], v[16:19]
	ds_read_b128 v[46:49], v2 offset:384
	ds_read_b128 v[54:57], v2 offset:448
	ds_read_b128 v[66:69], v5 offset:448
	s_waitcnt lgkmcnt(0)
	s_barrier
	s_waitcnt vmcnt(17)
	ds_write_b128 v4, v[206:209]
	s_waitcnt vmcnt(16)
	ds_write_b128 v6, v[210:213]
	s_waitcnt vmcnt(15)
	ds_write_b128 v8, v[214:217]
	s_waitcnt vmcnt(14)
	ds_write_b128 v10, v[218:221]
	s_waitcnt vmcnt(13)
	ds_write_b128 v12, v[120:123]
	s_waitcnt vmcnt(12)
	ds_write_b128 v14, v[124:127]
	s_waitcnt lgkmcnt(0)
	s_barrier
	v_mfma_f32_16x16x32_f16 v[16:19], v[50:53], v[58:61], v[16:19]
	v_mfma_f32_16x16x32_f16 v[16:19], v[62:65], v[46:49], v[16:19]
	ds_read_b128 v[46:49], v5
	v_mfma_f32_16x16x32_f16 v[16:19], v[66:69], v[54:57], v[16:19]
	ds_read_b128 v[50:53], v5 offset:64
	ds_read_b128 v[54:57], v2
	ds_read_b128 v[58:61], v2 offset:64
	s_waitcnt lgkmcnt(1)
	v_mfma_f32_16x16x32_f16 v[16:19], v[46:49], v[54:57], v[16:19]
	ds_read_b128 v[46:49], v5 offset:128
	ds_read_b128 v[54:57], v5 offset:192
	s_waitcnt lgkmcnt(2)
	v_mfma_f32_16x16x32_f16 v[16:19], v[50:53], v[58:61], v[16:19]
	ds_read_b128 v[50:53], v2 offset:128
	ds_read_b128 v[58:61], v2 offset:192
	ds_read_b128 v[62:65], v5 offset:256
	s_waitcnt lgkmcnt(2)
	v_mfma_f32_16x16x32_f16 v[16:19], v[46:49], v[50:53], v[16:19]
	ds_read_b128 v[46:49], v2 offset:256
	ds_read_b128 v[50:53], v2 offset:320
	ds_read_b128 v[66:69], v5 offset:320
	s_waitcnt lgkmcnt(4)
	v_mfma_f32_16x16x32_f16 v[16:19], v[54:57], v[58:61], v[16:19]
	ds_read_b128 v[54:57], v2 offset:384
	ds_read_b128 v[58:61], v2 offset:448
	ds_read_b128 v[70:73], v5 offset:384
	ds_read_b128 v[74:77], v5 offset:448
	s_waitcnt lgkmcnt(0)
	s_barrier
	s_waitcnt vmcnt(11)
	ds_write_b128 v4, v[136:139]
	s_waitcnt vmcnt(10)
	ds_write_b128 v6, v[140:143]
	s_waitcnt vmcnt(9)
	ds_write_b128 v8, v[144:147]
	s_waitcnt vmcnt(8)
	ds_write_b128 v10, v[148:151]
	s_waitcnt vmcnt(7)
	ds_write_b128 v12, v[152:155]
	s_waitcnt vmcnt(6)
	ds_write_b128 v14, v[156:159]
	s_waitcnt lgkmcnt(0)
	s_barrier
	v_mfma_f32_16x16x32_f16 v[16:19], v[62:65], v[46:49], v[16:19]
	ds_read_b128 v[46:49], v5
	v_mfma_f32_16x16x32_f16 v[16:19], v[66:69], v[50:53], v[16:19]
	v_mfma_f32_16x16x32_f16 v[16:19], v[70:73], v[54:57], v[16:19]
	ds_read_b128 v[50:53], v2
	ds_read_b128 v[54:57], v5 offset:64
	v_mfma_f32_16x16x32_f16 v[16:19], v[74:77], v[58:61], v[16:19]
	ds_read_b128 v[58:61], v2 offset:64
	ds_read_b128 v[62:65], v5 offset:128
	s_waitcnt lgkmcnt(3)
	v_mfma_f32_16x16x32_f16 v[16:19], v[46:49], v[50:53], v[16:19]
	ds_read_b128 v[46:49], v2 offset:128
	ds_read_b128 v[50:53], v5 offset:192
	s_waitcnt lgkmcnt(3)
	v_mfma_f32_16x16x32_f16 v[16:19], v[54:57], v[58:61], v[16:19]
	ds_read_b128 v[54:57], v2 offset:192
	ds_read_b128 v[58:61], v5 offset:256
	s_waitcnt lgkmcnt(3)
	v_mfma_f32_16x16x32_f16 v[16:19], v[62:65], v[46:49], v[16:19]
	ds_read_b128 v[46:49], v2 offset:256
	ds_read_b128 v[62:65], v2 offset:320
	ds_read_b128 v[66:69], v5 offset:320
	s_waitcnt lgkmcnt(4)
	v_mfma_f32_16x16x32_f16 v[16:19], v[50:53], v[54:57], v[16:19]
	ds_read_b128 v[50:53], v2 offset:384
	ds_read_b128 v[54:57], v2 offset:448
	ds_read_b128 v[70:73], v5 offset:384
	ds_read_b128 v[74:77], v5 offset:448
	s_waitcnt lgkmcnt(0)
	s_barrier
	v_mfma_f32_16x16x32_f16 v[16:19], v[58:61], v[46:49], v[16:19]
	s_waitcnt vmcnt(5)
	ds_write_b128 v4, v[178:181]
	s_waitcnt vmcnt(4)
	ds_write_b128 v6, v[182:185]
	s_waitcnt vmcnt(3)
	ds_write_b128 v8, v[186:189]
	s_waitcnt vmcnt(2)
	ds_write_b128 v10, v[190:193]
	s_waitcnt vmcnt(1)
	ds_write_b128 v12, v[194:197]
	s_waitcnt vmcnt(0)
	ds_write_b128 v14, v[198:201]
	v_mfma_f32_16x16x32_f16 v[16:19], v[66:69], v[62:65], v[16:19]
	s_waitcnt lgkmcnt(0)
	s_barrier
	v_add_u32_e32 v234, s15, v3
	v_ashrrev_i32_e32 v235, 31, v234
	v_lshlrev_b64 v[236:237], 10, v[0:1]
	v_lshl_add_u64 v[236:237], v[236:237], 0, v[234:235]
	v_lshl_add_u64 v[238:239], v[236:237], 2, s[38:39]
	v_lshlrev_b64 v[234:235], 2, v[234:235]
	global_load_dwordx4 v[226:229], v[238:239], off
	v_lshl_add_u64 v[238:239], s[2:3], 0, v[234:235]
	global_load_dwordx4 v[222:225], v[238:239], off
	v_lshl_add_u64 v[238:239], s[4:5], 0, v[234:235]
	global_load_dwordx4 v[230:233], v[238:239], off
	ds_read_b128 v[6:9], v5
	v_mfma_f32_16x16x32_f16 v[10:13], v[70:73], v[50:53], v[16:19]
	s_nop 3
	ds_read_b128 v[14:17], v2
	ds_read_b128 v[18:21], v5 offset:64
	ds_read_b128 v[22:25], v2 offset:64
	ds_read_b128 v[30:33], v5 offset:128
	v_add_u32_e32 v26, s15, v3
	v_mfma_f32_16x16x32_f16 v[10:13], v[74:77], v[54:57], v[10:13]
	v_lshlrev_b64 v[34:35], 10, v[0:1]
	v_ashrrev_i32_e32 v27, 31, v26
	v_lshl_add_u64 v[34:35], v[34:35], 0, v[26:27]
	s_waitcnt lgkmcnt(3)
	v_mfma_f32_16x16x32_f16 v[6:9], v[6:9], v[14:17], v[10:13]
	s_nop 2
	ds_read_b128 v[10:13], v2 offset:128
	ds_read_b128 v[14:17], v5 offset:192
	v_lshlrev_b64 v[26:27], 2, v[26:27]
	v_lshl_add_u64 v[36:37], v[34:35], 2, s[38:39]
	s_waitcnt lgkmcnt(3)
	v_mfma_f32_16x16x32_f16 v[6:9], v[18:21], v[22:25], v[6:9]
	ds_read_b128 v[18:21], v2 offset:192
	ds_read_b128 v[22:25], v5 offset:256
	s_waitcnt lgkmcnt(3)
	v_mfma_f32_16x16x32_f16 v[6:9], v[30:33], v[10:13], v[6:9]
	ds_read_b128 v[10:13], v2 offset:256
	ds_read_b128 v[30:33], v5 offset:320
	s_waitcnt lgkmcnt(3)
	v_mfma_f32_16x16x32_f16 v[6:9], v[14:17], v[18:21], v[6:9]
	ds_read_b128 v[14:17], v2 offset:320
	ds_read_b128 v[18:21], v5 offset:384
	s_waitcnt lgkmcnt(3)
	v_mfma_f32_16x16x32_f16 v[6:9], v[22:25], v[10:13], v[6:9]
	ds_read_b128 v[10:13], v2 offset:384
	v_lshl_add_u64 v[22:23], s[2:3], 0, v[26:27]
	s_waitcnt lgkmcnt(2)
	v_mfma_f32_16x16x32_f16 v[6:9], v[30:33], v[14:17], v[6:9]
	ds_read_b128 v[14:17], v2 offset:448
	ds_read_b128 v[2:5], v5 offset:448
	s_nop 0
	s_waitcnt lgkmcnt(2)
	v_mfma_f32_16x16x32_f16 v[6:9], v[18:21], v[10:13], v[6:9]
	s_nop 0
	v_lshl_add_u64 v[18:19], s[4:5], 0, v[26:27]
	s_waitcnt lgkmcnt(0)
	v_mfma_f32_16x16x32_f16 v[2:5], v[2:5], v[14:17], v[6:9]
	s_waitcnt vmcnt(0)
	s_nop 2
	v_pk_mul_f32 v[6:7], v[224:225], 0.5 op_sel_hi:[1,0]
	v_pk_mul_f32 v[8:9], v[222:223], 0.5 op_sel_hi:[1,0]
	s_waitcnt vmcnt(0)
	s_nop 0
	v_pk_fma_f32 v[6:7], v[4:5], v[6:7], v[228:229]
	v_pk_fma_f32 v[4:5], v[2:3], v[8:9], v[226:227]
	global_store_dwordx4 v[36:37], v[4:7], off
	s_nop 0
	v_mul_f32_e32 v2, v5, v5
	v_mul_f32_e32 v3, v7, v7
	v_fmac_f32_e32 v2, v4, v4
	v_fmac_f32_e32 v3, v6, v6
	v_add_f32_e32 v2, v2, v3
	ds_bpermute_b32 v3, v134, v2
	v_lshl_add_u64 v[12:13], v[34:35], 1, s[42:43]
	s_waitcnt lgkmcnt(0)
	v_add_f32_e32 v2, v2, v3
	ds_bpermute_b32 v3, v135, v2
	s_nop 0
	v_pk_mul_f32 v[6:7], v[232:233], v[6:7]
	v_pk_mul_f32 v[4:5], v[230:231], v[4:5]
	s_nop 0
	v_cvt_pk_f16_f32 v4, v4, v5
	v_cvt_pk_f16_f32 v5, v6, v7
	global_store_dwordx2 v[12:13], v[4:5], off
	s_and_saveexec_b64 s[14:15], vcc
	s_cbranch_execz .LBB0_1017
	v_lshlrev_b32_e32 v0, 2, v0
	s_waitcnt lgkmcnt(0)
	v_add_f32_e32 v2, v2, v3
	global_atomic_add_f32 v0, v2, s[12:13]
	s_branch .LBB0_1017

.LBB0_1244:
	v_mov_b32_e32 v28, v176
	s_and_b32 s4, s20, 0x1e0
	v_add_u32_e32 v8, s14, v28
	s_and_b32 s5, s18, 0xffffffc0
	s_bitset1_b32 s4, 14
	s_sub_i32 s26, s5, 32
	v_lshlrev_b32_e32 v0, 4, v28
	v_ashrrev_i32_e32 v9, 5, v8
	v_and_b32_e32 v0, 0x1f0, v0
	v_mov_b32_e32 v10, s26
	v_mov_b32_e32 v11, s4
	v_cmp_gt_i32_e32 vcc, 32, v9
	v_lshl_add_u64 v[2:3], s[10:11], 0, v[0:1]
	v_lshl_add_u64 v[4:5], s[36:37], 0, v[0:1]
	v_cndmask_b32_e32 v6, v10, v11, vcc
	v_add_u32_e32 v12, v6, v9
	v_cndmask_b32_e32 v7, v3, v5, vcc
	v_cndmask_b32_e32 v6, v2, v4, vcc
	v_mad_i64_i32 v[18:19], s[26:27], v12, s22, v[6:7]
	v_add_u32_e32 v6, 0x200, v8
	v_ashrrev_i32_e32 v12, 5, v6
	v_cmp_gt_i32_e32 vcc, 32, v12
	v_add_u32_e32 v0, 0, v0
	s_or_b32 s5, s5, s16
	v_cndmask_b32_e32 v6, v10, v11, vcc
	v_add_u32_e32 v13, v6, v12
	v_cndmask_b32_e32 v7, v3, v5, vcc
	v_cndmask_b32_e32 v6, v2, v4, vcc
	v_mad_i64_i32 v[16:17], s[26:27], v13, s22, v[6:7]
	v_add_u32_e32 v6, 0x400, v8
	v_ashrrev_i32_e32 v13, 5, v6
	v_cmp_gt_i32_e32 vcc, 32, v13
	s_add_i32 s4, s4, s15
	s_nop 0
	v_cndmask_b32_e32 v6, v10, v11, vcc
	v_add_u32_e32 v14, v6, v13
	v_cndmask_b32_e32 v7, v3, v5, vcc
	v_cndmask_b32_e32 v6, v2, v4, vcc
	v_mad_i64_i32 v[20:21], s[26:27], v14, s22, v[6:7]
	v_add_u32_e32 v6, 0x600, v8
	v_ashrrev_i32_e32 v14, 5, v6
	v_cmp_gt_i32_e32 vcc, 32, v14
	s_nop 1
	v_cndmask_b32_e32 v6, v10, v11, vcc
	v_add_u32_e32 v15, v6, v14
	v_cndmask_b32_e32 v7, v3, v5, vcc
	v_cndmask_b32_e32 v6, v2, v4, vcc
	v_mad_i64_i32 v[22:23], s[26:27], v15, s22, v[6:7]
	v_add_u32_e32 v6, 0x800, v8
	v_ashrrev_i32_e32 v15, 5, v6
	v_cmp_gt_i32_e32 vcc, 32, v15
	s_nop 1
	v_cndmask_b32_e32 v6, v10, v11, vcc
	v_add_u32_e32 v24, v6, v15
	v_cndmask_b32_e32 v7, v3, v5, vcc
	v_cndmask_b32_e32 v6, v2, v4, vcc
	v_mad_i64_i32 v[24:25], s[26:27], v24, s22, v[6:7]
	v_add_u32_e32 v6, 0xa00, v8
	v_ashrrev_i32_e32 v29, 5, v6
	v_cmp_gt_i32_e32 vcc, 32, v29
	s_nop 1
	v_cndmask_b32_e32 v6, v10, v11, vcc
	v_add_u32_e32 v6, v6, v29
	v_cndmask_b32_e32 v3, v3, v5, vcc
	v_cndmask_b32_e32 v2, v2, v4, vcc
	v_mad_i64_i32 v[26:27], s[26:27], v6, s22, v[2:3]
	global_load_dwordx4 v[136:139], v[18:19], off
	global_load_dwordx4 v[140:143], v[16:17], off
	global_load_dwordx4 v[144:147], v[20:21], off
	global_load_dwordx4 v[148:151], v[22:23], off
	global_load_dwordx4 v[152:155], v[24:25], off
	global_load_dwordx4 v[156:159], v[26:27], off
	global_load_dwordx4 v[178:181], v[18:19], off offset:512
	global_load_dwordx4 v[182:185], v[16:17], off offset:512
	global_load_dwordx4 v[186:189], v[20:21], off offset:512
	global_load_dwordx4 v[190:193], v[22:23], off offset:512
	global_load_dwordx4 v[194:197], v[24:25], off offset:512
	global_load_dwordx4 v[198:201], v[26:27], off offset:512
	global_load_dwordx4 v[206:209], v[18:19], off offset:1024
	global_load_dwordx4 v[210:213], v[16:17], off offset:1024
	global_load_dwordx4 v[214:217], v[20:21], off offset:1024
	global_load_dwordx4 v[218:221], v[22:23], off offset:1024
	global_load_dwordx4 v[120:123], v[24:25], off offset:1024
	global_load_dwordx4 v[124:127], v[26:27], off offset:1024
	v_mov_b32_e32 v112, 0x1000
	v_mov_b32_e32 v113, 0
	v_lshl_add_u64 v[128:129], v[18:19], 0, v[112:113]
	v_lshl_add_u64 v[130:131], v[16:17], 0, v[112:113]
	v_lshl_add_u64 v[132:133], v[20:21], 0, v[112:113]
	v_lshl_add_u64 v[106:107], v[22:23], 0, v[112:113]
	v_lshl_add_u64 v[108:109], v[24:25], 0, v[112:113]
	v_lshl_add_u64 v[110:111], v[26:27], 0, v[112:113]
	v_mad_u64_u32 v[4:5], s[26:27], v9, s23, v[0:1]
	v_mad_u64_u32 v[6:7], s[26:27], v12, s23, v[0:1]
	v_mad_u64_u32 v[8:9], s[26:27], v13, s23, v[0:1]
	v_mad_u64_u32 v[10:11], s[26:27], v14, s23, v[0:1]
	v_mad_u64_u32 v[12:13], s[26:27], v15, s23, v[0:1]
	v_mad_u64_u32 v[14:15], s[26:27], v29, s23, v[0:1]
	s_barrier
	v_and_b32_e32 v0, 15, v28
	v_and_b32_e32 v2, -16, v28
	v_add_u32_e32 v2, 0, v2
	v_or_b32_e32 v5, s17, v0
	v_mad_u32_u24 v5, v5, s23, v2
	v_or_b32_e32 v3, s15, v0
	v_mad_u64_u32 v[2:3], s[26:27], v3, s23, v[2:3]
	v_ashrrev_i32_e32 v3, 2, v28
	v_and_b32_e32 v3, -4, v3
	v_or_b32_e32 v0, s4, v0
	s_waitcnt vmcnt(17)
	ds_write_b128 v4, v[136:139]
	s_waitcnt vmcnt(16)
	ds_write_b128 v6, v[140:143]
	s_waitcnt vmcnt(15)
	ds_write_b128 v8, v[144:147]
	s_waitcnt vmcnt(14)
	ds_write_b128 v10, v[148:151]
	s_waitcnt vmcnt(13)
	ds_write_b128 v12, v[152:155]
	s_waitcnt vmcnt(12)
	ds_write_b128 v14, v[156:159]
	s_waitcnt lgkmcnt(0)
	s_barrier
	global_load_dwordx4 v[136:139], v[18:19], off offset:1536
	global_load_dwordx4 v[140:143], v[16:17], off offset:1536
	global_load_dwordx4 v[144:147], v[20:21], off offset:1536
	global_load_dwordx4 v[148:151], v[22:23], off offset:1536
	global_load_dwordx4 v[152:155], v[24:25], off offset:1536
	global_load_dwordx4 v[156:159], v[26:27], off offset:1536
	ds_read_b128 v[54:57], v5
	ds_read_b128 v[58:61], v5 offset:64
	ds_read_b128 v[62:65], v2
	ds_read_b128 v[66:69], v2 offset:64
	s_waitcnt lgkmcnt(1)
	v_mfma_f32_16x16x32_f16 v[54:57], v[54:57], v[62:65], 0
	ds_read_b128 v[62:65], v5 offset:128
	ds_read_b128 v[70:73], v5 offset:192
	s_waitcnt lgkmcnt(2)
	v_mfma_f32_16x16x32_f16 v[54:57], v[58:61], v[66:69], v[54:57]
	ds_read_b128 v[58:61], v2 offset:128
	ds_read_b128 v[66:69], v2 offset:192
	s_waitcnt lgkmcnt(1)
	v_mfma_f32_16x16x32_f16 v[54:57], v[62:65], v[58:61], v[54:57]
	ds_read_b128 v[58:61], v5 offset:256
	ds_read_b128 v[62:65], v5 offset:320
	s_waitcnt lgkmcnt(2)
	v_mfma_f32_16x16x32_f16 v[54:57], v[70:73], v[66:69], v[54:57]
	ds_read_b128 v[66:69], v2 offset:256
	ds_read_b128 v[70:73], v2 offset:320
	ds_read_b128 v[74:77], v5 offset:384
	s_waitcnt lgkmcnt(2)
	v_mfma_f32_16x16x32_f16 v[54:57], v[58:61], v[66:69], v[54:57]
	ds_read_b128 v[58:61], v2 offset:384
	ds_read_b128 v[66:69], v2 offset:448
	ds_read_b128 v[78:81], v5 offset:448
	s_waitcnt lgkmcnt(0)
	s_barrier
	s_waitcnt vmcnt(17)
	ds_write_b128 v4, v[178:181]
	s_waitcnt vmcnt(16)
	ds_write_b128 v6, v[182:185]
	s_waitcnt vmcnt(15)
	ds_write_b128 v8, v[186:189]
	s_waitcnt vmcnt(14)
	ds_write_b128 v10, v[190:193]
	s_waitcnt vmcnt(13)
	ds_write_b128 v12, v[194:197]
	s_waitcnt vmcnt(12)
	ds_write_b128 v14, v[198:201]
	s_waitcnt lgkmcnt(0)
	s_barrier
	global_load_dwordx4 v[178:181], v[18:19], off offset:2048
	global_load_dwordx4 v[182:185], v[16:17], off offset:2048
	global_load_dwordx4 v[186:189], v[20:21], off offset:2048
	global_load_dwordx4 v[190:193], v[22:23], off offset:2048
	global_load_dwordx4 v[194:197], v[24:25], off offset:2048
	global_load_dwordx4 v[198:201], v[26:27], off offset:2048
	v_mfma_f32_16x16x32_f16 v[54:57], v[62:65], v[70:73], v[54:57]
	v_mfma_f32_16x16x32_f16 v[54:57], v[74:77], v[58:61], v[54:57]
	ds_read_b128 v[58:61], v5
	v_mfma_f32_16x16x32_f16 v[54:57], v[78:81], v[66:69], v[54:57]
	ds_read_b128 v[62:65], v5 offset:64
	ds_read_b128 v[66:69], v2
	ds_read_b128 v[70:73], v2 offset:64
	s_waitcnt lgkmcnt(1)
	v_mfma_f32_16x16x32_f16 v[54:57], v[58:61], v[66:69], v[54:57]
	ds_read_b128 v[58:61], v5 offset:128
	ds_read_b128 v[66:69], v5 offset:192
	s_waitcnt lgkmcnt(2)
	v_mfma_f32_16x16x32_f16 v[54:57], v[62:65], v[70:73], v[54:57]
	ds_read_b128 v[62:65], v2 offset:128
	ds_read_b128 v[70:73], v2 offset:192
	s_waitcnt lgkmcnt(1)
	v_mfma_f32_16x16x32_f16 v[54:57], v[58:61], v[62:65], v[54:57]
	ds_read_b128 v[58:61], v5 offset:256
	ds_read_b128 v[62:65], v5 offset:320
	s_waitcnt lgkmcnt(2)
	v_mfma_f32_16x16x32_f16 v[54:57], v[66:69], v[70:73], v[54:57]
	ds_read_b128 v[66:69], v2 offset:256
	ds_read_b128 v[70:73], v2 offset:320
	ds_read_b128 v[74:77], v5 offset:384
	s_waitcnt lgkmcnt(2)
	v_mfma_f32_16x16x32_f16 v[54:57], v[58:61], v[66:69], v[54:57]
	ds_read_b128 v[58:61], v2 offset:384
	ds_read_b128 v[66:69], v2 offset:448
	ds_read_b128 v[78:81], v5 offset:448
	s_waitcnt lgkmcnt(0)
	s_barrier
	s_waitcnt vmcnt(17)
	ds_write_b128 v4, v[206:209]
	s_waitcnt vmcnt(16)
	ds_write_b128 v6, v[210:213]
	s_waitcnt vmcnt(15)
	ds_write_b128 v8, v[214:217]
	s_waitcnt vmcnt(14)
	ds_write_b128 v10, v[218:221]
	s_waitcnt vmcnt(13)
	ds_write_b128 v12, v[120:123]
	s_waitcnt vmcnt(12)
	ds_write_b128 v14, v[124:127]
	s_waitcnt lgkmcnt(0)
	s_barrier
	global_load_dwordx4 v[206:209], v[18:19], off offset:2560
	global_load_dwordx4 v[210:213], v[16:17], off offset:2560
	global_load_dwordx4 v[214:217], v[20:21], off offset:2560
	global_load_dwordx4 v[218:221], v[22:23], off offset:2560
	global_load_dwordx4 v[120:123], v[24:25], off offset:2560
	global_load_dwordx4 v[124:127], v[26:27], off offset:2560
	v_mfma_f32_16x16x32_f16 v[54:57], v[62:65], v[70:73], v[54:57]
	v_mfma_f32_16x16x32_f16 v[54:57], v[74:77], v[58:61], v[54:57]
	ds_read_b128 v[58:61], v5
	v_mfma_f32_16x16x32_f16 v[54:57], v[78:81], v[66:69], v[54:57]
	ds_read_b128 v[62:65], v5 offset:64
	ds_read_b128 v[66:69], v2
	ds_read_b128 v[70:73], v2 offset:64
	s_waitcnt lgkmcnt(1)
	v_mfma_f32_16x16x32_f16 v[54:57], v[58:61], v[66:69], v[54:57]
	ds_read_b128 v[58:61], v5 offset:128
	ds_read_b128 v[66:69], v5 offset:192
	s_waitcnt lgkmcnt(2)
	v_mfma_f32_16x16x32_f16 v[54:57], v[62:65], v[70:73], v[54:57]
	ds_read_b128 v[62:65], v2 offset:128
	ds_read_b128 v[70:73], v2 offset:192
	s_waitcnt lgkmcnt(1)
	v_mfma_f32_16x16x32_f16 v[54:57], v[58:61], v[62:65], v[54:57]
	ds_read_b128 v[58:61], v5 offset:256
	ds_read_b128 v[62:65], v5 offset:320
	s_waitcnt lgkmcnt(2)
	v_mfma_f32_16x16x32_f16 v[54:57], v[66:69], v[70:73], v[54:57]
	ds_read_b128 v[66:69], v2 offset:256
	ds_read_b128 v[70:73], v2 offset:320
	ds_read_b128 v[74:77], v5 offset:384
	s_waitcnt lgkmcnt(2)
	v_mfma_f32_16x16x32_f16 v[54:57], v[58:61], v[66:69], v[54:57]
	ds_read_b128 v[58:61], v2 offset:384
	ds_read_b128 v[66:69], v2 offset:448
	ds_read_b128 v[78:81], v5 offset:448
	s_waitcnt lgkmcnt(0)
	s_barrier
	s_waitcnt vmcnt(17)
	ds_write_b128 v4, v[136:139]
	s_waitcnt vmcnt(16)
	ds_write_b128 v6, v[140:143]
	s_waitcnt vmcnt(15)
	ds_write_b128 v8, v[144:147]
	s_waitcnt vmcnt(14)
	ds_write_b128 v10, v[148:151]
	s_waitcnt vmcnt(13)
	ds_write_b128 v12, v[152:155]
	s_waitcnt vmcnt(12)
	ds_write_b128 v14, v[156:159]
	s_waitcnt lgkmcnt(0)
	s_barrier
	global_load_dwordx4 v[136:139], v[18:19], off offset:3072
	global_load_dwordx4 v[140:143], v[16:17], off offset:3072
	global_load_dwordx4 v[144:147], v[20:21], off offset:3072
	global_load_dwordx4 v[148:151], v[22:23], off offset:3072
	global_load_dwordx4 v[152:155], v[24:25], off offset:3072
	global_load_dwordx4 v[156:159], v[26:27], off offset:3072
	v_mfma_f32_16x16x32_f16 v[54:57], v[62:65], v[70:73], v[54:57]
	v_mfma_f32_16x16x32_f16 v[54:57], v[74:77], v[58:61], v[54:57]
	ds_read_b128 v[58:61], v5
	v_mfma_f32_16x16x32_f16 v[54:57], v[78:81], v[66:69], v[54:57]
	ds_read_b128 v[62:65], v5 offset:64
	ds_read_b128 v[66:69], v2
	ds_read_b128 v[70:73], v2 offset:64
	s_waitcnt lgkmcnt(1)
	v_mfma_f32_16x16x32_f16 v[54:57], v[58:61], v[66:69], v[54:57]
	ds_read_b128 v[58:61], v5 offset:128
	ds_read_b128 v[66:69], v5 offset:192
	s_waitcnt lgkmcnt(2)
	v_mfma_f32_16x16x32_f16 v[54:57], v[62:65], v[70:73], v[54:57]
	ds_read_b128 v[62:65], v2 offset:128
	ds_read_b128 v[70:73], v2 offset:192
	s_waitcnt lgkmcnt(1)
	v_mfma_f32_16x16x32_f16 v[54:57], v[58:61], v[62:65], v[54:57]
	ds_read_b128 v[58:61], v5 offset:256
	ds_read_b128 v[62:65], v5 offset:320
	s_waitcnt lgkmcnt(2)
	v_mfma_f32_16x16x32_f16 v[54:57], v[66:69], v[70:73], v[54:57]
	ds_read_b128 v[66:69], v2 offset:256
	ds_read_b128 v[70:73], v2 offset:320
	ds_read_b128 v[74:77], v5 offset:384
	s_waitcnt lgkmcnt(2)
	v_mfma_f32_16x16x32_f16 v[54:57], v[58:61], v[66:69], v[54:57]
	ds_read_b128 v[58:61], v2 offset:384
	ds_read_b128 v[66:69], v2 offset:448
	ds_read_b128 v[78:81], v5 offset:448
	s_waitcnt lgkmcnt(0)
	s_barrier
	s_waitcnt vmcnt(17)
	ds_write_b128 v4, v[178:181]
	s_waitcnt vmcnt(16)
	ds_write_b128 v6, v[182:185]
	s_waitcnt vmcnt(15)
	ds_write_b128 v8, v[186:189]
	s_waitcnt vmcnt(14)
	ds_write_b128 v10, v[190:193]
	s_waitcnt vmcnt(13)
	ds_write_b128 v12, v[194:197]
	s_waitcnt vmcnt(12)
	ds_write_b128 v14, v[198:201]
	s_waitcnt lgkmcnt(0)
	s_barrier
	global_load_dwordx4 v[178:181], v[18:19], off offset:3584
	global_load_dwordx4 v[182:185], v[16:17], off offset:3584
	global_load_dwordx4 v[186:189], v[20:21], off offset:3584
	global_load_dwordx4 v[190:193], v[22:23], off offset:3584
	global_load_dwordx4 v[194:197], v[24:25], off offset:3584
	global_load_dwordx4 v[198:201], v[26:27], off offset:3584
	v_mfma_f32_16x16x32_f16 v[54:57], v[62:65], v[70:73], v[54:57]
	v_mfma_f32_16x16x32_f16 v[54:57], v[74:77], v[58:61], v[54:57]
	ds_read_b128 v[58:61], v5
	v_mfma_f32_16x16x32_f16 v[54:57], v[78:81], v[66:69], v[54:57]
	ds_read_b128 v[62:65], v5 offset:64
	ds_read_b128 v[66:69], v2
	ds_read_b128 v[70:73], v2 offset:64
	s_waitcnt lgkmcnt(1)
	v_mfma_f32_16x16x32_f16 v[54:57], v[58:61], v[66:69], v[54:57]
	ds_read_b128 v[58:61], v5 offset:128
	ds_read_b128 v[66:69], v5 offset:192
	s_waitcnt lgkmcnt(2)
	v_mfma_f32_16x16x32_f16 v[54:57], v[62:65], v[70:73], v[54:57]
	ds_read_b128 v[62:65], v2 offset:128
	ds_read_b128 v[70:73], v2 offset:192
	s_waitcnt lgkmcnt(1)
	v_mfma_f32_16x16x32_f16 v[54:57], v[58:61], v[62:65], v[54:57]
	ds_read_b128 v[58:61], v5 offset:256
	ds_read_b128 v[62:65], v5 offset:320
	s_waitcnt lgkmcnt(2)
	v_mfma_f32_16x16x32_f16 v[54:57], v[66:69], v[70:73], v[54:57]
	ds_read_b128 v[66:69], v2 offset:256
	ds_read_b128 v[70:73], v2 offset:320
	ds_read_b128 v[74:77], v5 offset:384
	s_waitcnt lgkmcnt(2)
	v_mfma_f32_16x16x32_f16 v[54:57], v[58:61], v[66:69], v[54:57]
	ds_read_b128 v[58:61], v2 offset:384
	ds_read_b128 v[66:69], v2 offset:448
	ds_read_b128 v[78:81], v5 offset:448
	s_waitcnt lgkmcnt(0)
	s_barrier
	s_waitcnt vmcnt(17)
	ds_write_b128 v4, v[206:209]
	s_waitcnt vmcnt(16)
	ds_write_b128 v6, v[210:213]
	s_waitcnt vmcnt(15)
	ds_write_b128 v8, v[214:217]
	s_waitcnt vmcnt(14)
	ds_write_b128 v10, v[218:221]
	s_waitcnt vmcnt(13)
	ds_write_b128 v12, v[120:123]
	s_waitcnt vmcnt(12)
	ds_write_b128 v14, v[124:127]
	s_waitcnt lgkmcnt(0)
	s_barrier
	global_load_dwordx4 v[206:209], v[128:129], off
	global_load_dwordx4 v[210:213], v[130:131], off
	global_load_dwordx4 v[214:217], v[132:133], off
	global_load_dwordx4 v[218:221], v[106:107], off
	global_load_dwordx4 v[120:123], v[108:109], off
	global_load_dwordx4 v[124:127], v[110:111], off
	v_mfma_f32_16x16x32_f16 v[54:57], v[62:65], v[70:73], v[54:57]
	v_mfma_f32_16x16x32_f16 v[54:57], v[74:77], v[58:61], v[54:57]
	ds_read_b128 v[58:61], v5
	v_mfma_f32_16x16x32_f16 v[54:57], v[78:81], v[66:69], v[54:57]
	ds_read_b128 v[62:65], v2
	ds_read_b128 v[66:69], v2 offset:64
	ds_read_b128 v[70:73], v5 offset:64
	ds_read_b128 v[74:77], v2 offset:128
	ds_read_b128 v[78:81], v2 offset:192
	ds_read_b128 v[82:85], v5 offset:128
	ds_read_b128 v[86:89], v5 offset:192
	s_waitcnt lgkmcnt(6)
	v_mfma_f32_16x16x32_f16 v[54:57], v[58:61], v[62:65], v[54:57]
	ds_read_b128 v[58:61], v2 offset:256
	ds_read_b128 v[62:65], v2 offset:320
	ds_read_b128 v[90:93], v5 offset:256
	ds_read_b128 v[94:97], v5 offset:320
	s_waitcnt lgkmcnt(8)
	v_mfma_f32_16x16x32_f16 v[54:57], v[70:73], v[66:69], v[54:57]
	ds_read_b128 v[66:69], v2 offset:384
	ds_read_b128 v[70:73], v2 offset:448
	ds_read_b128 v[98:101], v5 offset:384
	ds_read_b128 v[102:105], v5 offset:448
	s_waitcnt lgkmcnt(0)
	s_barrier
	s_waitcnt vmcnt(17)
	ds_write_b128 v4, v[136:139]
	s_waitcnt vmcnt(16)
	ds_write_b128 v6, v[140:143]
	s_waitcnt vmcnt(15)
	ds_write_b128 v8, v[144:147]
	s_waitcnt vmcnt(14)
	ds_write_b128 v10, v[148:151]
	s_waitcnt vmcnt(13)
	ds_write_b128 v12, v[152:155]
	s_waitcnt vmcnt(12)
	ds_write_b128 v14, v[156:159]
	s_waitcnt lgkmcnt(0)
	s_barrier
	global_load_dwordx4 v[136:139], v[128:129], off offset:512
	global_load_dwordx4 v[140:143], v[130:131], off offset:512
	global_load_dwordx4 v[144:147], v[132:133], off offset:512
	global_load_dwordx4 v[148:151], v[106:107], off offset:512
	global_load_dwordx4 v[152:155], v[108:109], off offset:512
	global_load_dwordx4 v[156:159], v[110:111], off offset:512
	v_mfma_f32_16x16x32_f16 v[54:57], v[82:85], v[74:77], v[54:57]
	v_mfma_f32_16x16x32_f16 v[54:57], v[86:89], v[78:81], v[54:57]
	v_add_co_u32_e32 v78, vcc, s24, v18
	v_mfma_f32_16x16x32_f16 v[54:57], v[90:93], v[58:61], v[54:57]
	s_nop 0
	v_addc_co_u32_e32 v79, vcc, 0, v19, vcc
	v_add_co_u32_e32 v80, vcc, s24, v26
	v_mfma_f32_16x16x32_f16 v[54:57], v[94:97], v[62:65], v[54:57]
	s_nop 0
	v_addc_co_u32_e32 v81, vcc, 0, v27, vcc
	v_add_co_u32_e32 v82, vcc, s24, v24
	v_mfma_f32_16x16x32_f16 v[54:57], v[98:101], v[66:69], v[54:57]
	s_nop 0
	v_addc_co_u32_e32 v83, vcc, 0, v25, vcc
	ds_read_b128 v[24:27], v5
	v_mfma_f32_16x16x32_f16 v[54:57], v[102:105], v[70:73], v[54:57]
	ds_read_b128 v[58:61], v2
	ds_read_b128 v[62:65], v5 offset:64
	v_add_co_u32_e32 v84, vcc, s24, v22
	ds_read_b128 v[66:69], v2 offset:64
	s_nop 0
	v_addc_co_u32_e32 v85, vcc, 0, v23, vcc
	s_waitcnt lgkmcnt(2)
	v_mfma_f32_16x16x32_f16 v[22:25], v[24:27], v[58:61], v[54:57]
	s_nop 2
	ds_read_b128 v[54:57], v5 offset:128
	ds_read_b128 v[58:61], v2 offset:128
	ds_read_b128 v[70:73], v5 offset:192
	v_add_co_u32_e32 v86, vcc, s24, v20
	s_waitcnt lgkmcnt(3)
	v_mfma_f32_16x16x32_f16 v[22:25], v[62:65], v[66:69], v[22:25]
	v_addc_co_u32_e32 v87, vcc, 0, v21, vcc
	ds_read_b128 v[18:21], v2 offset:192
	s_waitcnt lgkmcnt(2)
	v_mfma_f32_16x16x32_f16 v[22:25], v[54:57], v[58:61], v[22:25]
	ds_read_b128 v[54:57], v2 offset:256
	ds_read_b128 v[58:61], v5 offset:256
	ds_read_b128 v[62:65], v5 offset:320
	v_add_co_u32_e32 v88, vcc, s24, v16
	s_waitcnt lgkmcnt(3)
	v_mfma_f32_16x16x32_f16 v[18:21], v[70:73], v[18:21], v[22:25]
	v_addc_co_u32_e32 v89, vcc, 0, v17, vcc
	s_nop 1
	ds_read_b128 v[22:25], v2 offset:320
	ds_read_b128 v[66:69], v5 offset:384
	s_waitcnt lgkmcnt(3)
	v_mfma_f32_16x16x32_f16 v[16:19], v[58:61], v[54:57], v[18:21]
	ds_read_b128 v[54:57], v2 offset:384
	ds_read_b128 v[58:61], v2 offset:448
	ds_read_b128 v[70:73], v5 offset:448
	s_waitcnt lgkmcnt(0)
	s_barrier
	v_mfma_f32_16x16x32_f16 v[16:19], v[62:65], v[22:25], v[16:19]
	s_waitcnt vmcnt(17)
	ds_write_b128 v4, v[178:181]
	s_waitcnt vmcnt(16)
	ds_write_b128 v6, v[182:185]
	s_waitcnt vmcnt(15)
	ds_write_b128 v8, v[186:189]
	s_waitcnt vmcnt(14)
	ds_write_b128 v10, v[190:193]
	s_waitcnt vmcnt(13)
	ds_write_b128 v12, v[194:197]
	s_waitcnt vmcnt(12)
	ds_write_b128 v14, v[198:201]
	s_waitcnt lgkmcnt(0)
	s_barrier
	global_load_dwordx4 v[178:181], v[128:129], off offset:1024
	global_load_dwordx4 v[182:185], v[130:131], off offset:1024
	global_load_dwordx4 v[186:189], v[132:133], off offset:1024
	global_load_dwordx4 v[190:193], v[106:107], off offset:1024
	global_load_dwordx4 v[194:197], v[108:109], off offset:1024
	global_load_dwordx4 v[198:201], v[110:111], off offset:1024
	ds_read_b128 v[46:49], v5
	v_mfma_f32_16x16x32_f16 v[16:19], v[66:69], v[54:57], v[16:19]
	v_cmp_gt_u32_e32 vcc, 16, v28
	v_mfma_f32_16x16x32_f16 v[16:19], v[70:73], v[58:61], v[16:19]
	ds_read_b128 v[50:53], v5 offset:64
	ds_read_b128 v[54:57], v2
	ds_read_b128 v[58:61], v2 offset:64
	s_waitcnt lgkmcnt(1)
	v_mfma_f32_16x16x32_f16 v[16:19], v[46:49], v[54:57], v[16:19]
	ds_read_b128 v[46:49], v5 offset:128
	ds_read_b128 v[54:57], v5 offset:192
	s_waitcnt lgkmcnt(2)
	v_mfma_f32_16x16x32_f16 v[16:19], v[50:53], v[58:61], v[16:19]
	ds_read_b128 v[50:53], v2 offset:128
	ds_read_b128 v[58:61], v2 offset:192
	s_waitcnt lgkmcnt(1)
	v_mfma_f32_16x16x32_f16 v[16:19], v[46:49], v[50:53], v[16:19]
	ds_read_b128 v[46:49], v5 offset:256
	ds_read_b128 v[50:53], v5 offset:320
	s_waitcnt lgkmcnt(2)
	v_mfma_f32_16x16x32_f16 v[16:19], v[54:57], v[58:61], v[16:19]
	ds_read_b128 v[54:57], v2 offset:256
	ds_read_b128 v[58:61], v2 offset:320
	ds_read_b128 v[62:65], v5 offset:384
	s_waitcnt lgkmcnt(2)
	v_mfma_f32_16x16x32_f16 v[16:19], v[46:49], v[54:57], v[16:19]
	ds_read_b128 v[46:49], v2 offset:384
	ds_read_b128 v[54:57], v2 offset:448
	ds_read_b128 v[66:69], v5 offset:448
	s_waitcnt lgkmcnt(0)
	s_barrier
	s_waitcnt vmcnt(17)
	ds_write_b128 v4, v[206:209]
	s_waitcnt vmcnt(16)
	ds_write_b128 v6, v[210:213]
	s_waitcnt vmcnt(15)
	ds_write_b128 v8, v[214:217]
	s_waitcnt vmcnt(14)
	ds_write_b128 v10, v[218:221]
	s_waitcnt vmcnt(13)
	ds_write_b128 v12, v[120:123]
	s_waitcnt vmcnt(12)
	ds_write_b128 v14, v[124:127]
	s_waitcnt lgkmcnt(0)
	s_barrier
	v_mfma_f32_16x16x32_f16 v[16:19], v[50:53], v[58:61], v[16:19]
	v_mfma_f32_16x16x32_f16 v[16:19], v[62:65], v[46:49], v[16:19]
	ds_read_b128 v[46:49], v5
	v_mfma_f32_16x16x32_f16 v[16:19], v[66:69], v[54:57], v[16:19]
	ds_read_b128 v[50:53], v5 offset:64
	ds_read_b128 v[54:57], v2
	ds_read_b128 v[58:61], v2 offset:64
	s_waitcnt lgkmcnt(1)
	v_mfma_f32_16x16x32_f16 v[16:19], v[46:49], v[54:57], v[16:19]
	ds_read_b128 v[46:49], v5 offset:128
	ds_read_b128 v[54:57], v5 offset:192
	s_waitcnt lgkmcnt(2)
	v_mfma_f32_16x16x32_f16 v[16:19], v[50:53], v[58:61], v[16:19]
	ds_read_b128 v[50:53], v2 offset:128
	ds_read_b128 v[58:61], v2 offset:192
	ds_read_b128 v[62:65], v5 offset:256
	s_waitcnt lgkmcnt(2)
	v_mfma_f32_16x16x32_f16 v[16:19], v[46:49], v[50:53], v[16:19]
	ds_read_b128 v[46:49], v2 offset:256
	ds_read_b128 v[50:53], v2 offset:320
	ds_read_b128 v[66:69], v5 offset:320
	s_waitcnt lgkmcnt(4)
	v_mfma_f32_16x16x32_f16 v[16:19], v[54:57], v[58:61], v[16:19]
	ds_read_b128 v[54:57], v2 offset:384
	ds_read_b128 v[58:61], v2 offset:448
	ds_read_b128 v[70:73], v5 offset:384
	ds_read_b128 v[74:77], v5 offset:448
	s_waitcnt lgkmcnt(0)
	s_barrier
	s_waitcnt vmcnt(11)
	ds_write_b128 v4, v[136:139]
	s_waitcnt vmcnt(10)
	ds_write_b128 v6, v[140:143]
	s_waitcnt vmcnt(9)
	ds_write_b128 v8, v[144:147]
	s_waitcnt vmcnt(8)
	ds_write_b128 v10, v[148:151]
	s_waitcnt vmcnt(7)
	ds_write_b128 v12, v[152:155]
	s_waitcnt vmcnt(6)
	ds_write_b128 v14, v[156:159]
	s_waitcnt lgkmcnt(0)
	s_barrier
	v_mfma_f32_16x16x32_f16 v[16:19], v[62:65], v[46:49], v[16:19]
	ds_read_b128 v[46:49], v5
	v_mfma_f32_16x16x32_f16 v[16:19], v[66:69], v[50:53], v[16:19]
	v_mfma_f32_16x16x32_f16 v[16:19], v[70:73], v[54:57], v[16:19]
	ds_read_b128 v[50:53], v2
	ds_read_b128 v[54:57], v5 offset:64
	v_mfma_f32_16x16x32_f16 v[16:19], v[74:77], v[58:61], v[16:19]
	ds_read_b128 v[58:61], v2 offset:64
	ds_read_b128 v[62:65], v5 offset:128
	s_waitcnt lgkmcnt(3)
	v_mfma_f32_16x16x32_f16 v[16:19], v[46:49], v[50:53], v[16:19]
	ds_read_b128 v[46:49], v2 offset:128
	ds_read_b128 v[50:53], v5 offset:192
	s_waitcnt lgkmcnt(3)
	v_mfma_f32_16x16x32_f16 v[16:19], v[54:57], v[58:61], v[16:19]
	ds_read_b128 v[54:57], v2 offset:192
	ds_read_b128 v[58:61], v5 offset:256
	s_waitcnt lgkmcnt(3)
	v_mfma_f32_16x16x32_f16 v[16:19], v[62:65], v[46:49], v[16:19]
	ds_read_b128 v[46:49], v2 offset:256
	ds_read_b128 v[62:65], v2 offset:320
	ds_read_b128 v[66:69], v5 offset:320
	s_waitcnt lgkmcnt(4)
	v_mfma_f32_16x16x32_f16 v[16:19], v[50:53], v[54:57], v[16:19]
	ds_read_b128 v[50:53], v2 offset:384
	ds_read_b128 v[54:57], v2 offset:448
	ds_read_b128 v[70:73], v5 offset:384
	ds_read_b128 v[74:77], v5 offset:448
	s_waitcnt lgkmcnt(0)
	s_barrier
	v_mfma_f32_16x16x32_f16 v[16:19], v[58:61], v[46:49], v[16:19]
	s_waitcnt vmcnt(5)
	ds_write_b128 v4, v[178:181]
	s_waitcnt vmcnt(4)
	ds_write_b128 v6, v[182:185]
	s_waitcnt vmcnt(3)
	ds_write_b128 v8, v[186:189]
	s_waitcnt vmcnt(2)
	ds_write_b128 v10, v[190:193]
	s_waitcnt vmcnt(1)
	ds_write_b128 v12, v[194:197]
	s_waitcnt vmcnt(0)
	ds_write_b128 v14, v[198:201]
	v_mfma_f32_16x16x32_f16 v[16:19], v[66:69], v[62:65], v[16:19]
	s_waitcnt lgkmcnt(0)
	s_barrier
	v_add_u32_e32 v234, s5, v3
	v_ashrrev_i32_e32 v235, 31, v234
	v_lshlrev_b64 v[236:237], 10, v[0:1]
	v_lshl_add_u64 v[236:237], v[236:237], 0, v[234:235]
	v_lshl_add_u64 v[238:239], v[236:237], 2, s[38:39]
	v_lshlrev_b64 v[234:235], 2, v[234:235]
	global_load_dwordx4 v[226:229], v[238:239], off
	v_lshl_add_u64 v[238:239], s[0:1], 0, v[234:235]
	global_load_dwordx4 v[222:225], v[238:239], off
	v_lshl_add_u64 v[238:239], s[2:3], 0, v[234:235]
	global_load_dwordx4 v[230:233], v[238:239], off
	ds_read_b128 v[6:9], v5
	v_mfma_f32_16x16x32_f16 v[10:13], v[70:73], v[50:53], v[16:19]
	s_nop 3
	ds_read_b128 v[14:17], v2
	ds_read_b128 v[18:21], v5 offset:64
	ds_read_b128 v[22:25], v2 offset:64
	ds_read_b128 v[30:33], v5 offset:128
	v_add_u32_e32 v26, s5, v3
	v_mfma_f32_16x16x32_f16 v[10:13], v[74:77], v[54:57], v[10:13]
	v_lshlrev_b64 v[34:35], 10, v[0:1]
	v_ashrrev_i32_e32 v27, 31, v26
	v_lshl_add_u64 v[34:35], v[34:35], 0, v[26:27]
	s_waitcnt lgkmcnt(3)
	v_mfma_f32_16x16x32_f16 v[6:9], v[6:9], v[14:17], v[10:13]
	s_nop 2
	ds_read_b128 v[10:13], v2 offset:128
	ds_read_b128 v[14:17], v5 offset:192
	v_lshlrev_b64 v[26:27], 2, v[26:27]
	v_lshl_add_u64 v[36:37], v[34:35], 2, s[38:39]
	s_waitcnt lgkmcnt(3)
	v_mfma_f32_16x16x32_f16 v[6:9], v[18:21], v[22:25], v[6:9]
	ds_read_b128 v[18:21], v2 offset:192
	ds_read_b128 v[22:25], v5 offset:256
	s_waitcnt lgkmcnt(3)
	v_mfma_f32_16x16x32_f16 v[6:9], v[30:33], v[10:13], v[6:9]
	ds_read_b128 v[10:13], v2 offset:256
	ds_read_b128 v[30:33], v5 offset:320
	s_waitcnt lgkmcnt(3)
	v_mfma_f32_16x16x32_f16 v[6:9], v[14:17], v[18:21], v[6:9]
	ds_read_b128 v[14:17], v2 offset:320
	ds_read_b128 v[18:21], v5 offset:384
	s_waitcnt lgkmcnt(3)
	v_mfma_f32_16x16x32_f16 v[6:9], v[22:25], v[10:13], v[6:9]
	ds_read_b128 v[10:13], v2 offset:384
	v_lshl_add_u64 v[22:23], s[0:1], 0, v[26:27]
	s_waitcnt lgkmcnt(2)
	v_mfma_f32_16x16x32_f16 v[6:9], v[30:33], v[14:17], v[6:9]
	ds_read_b128 v[14:17], v2 offset:448
	ds_read_b128 v[2:5], v5 offset:448
	s_nop 0
	s_waitcnt lgkmcnt(2)
	v_mfma_f32_16x16x32_f16 v[6:9], v[18:21], v[10:13], v[6:9]
	s_nop 0
	v_lshl_add_u64 v[18:19], s[2:3], 0, v[26:27]
	s_waitcnt lgkmcnt(0)
	v_mfma_f32_16x16x32_f16 v[2:5], v[2:5], v[14:17], v[6:9]
	s_waitcnt vmcnt(0)
	s_nop 2
	v_pk_mul_f32 v[6:7], v[224:225], 0.5 op_sel_hi:[1,0]
	v_pk_mul_f32 v[8:9], v[222:223], 0.5 op_sel_hi:[1,0]
	s_waitcnt vmcnt(0)
	s_nop 0
	v_pk_fma_f32 v[6:7], v[4:5], v[6:7], v[228:229]
	v_pk_fma_f32 v[4:5], v[2:3], v[8:9], v[226:227]
	global_store_dwordx4 v[36:37], v[4:7], off
	s_nop 0
	v_mul_f32_e32 v2, v5, v5
	v_mul_f32_e32 v3, v7, v7
	v_fmac_f32_e32 v2, v4, v4
	v_fmac_f32_e32 v3, v6, v6
	v_add_f32_e32 v2, v2, v3
	ds_bpermute_b32 v3, v134, v2
	v_lshl_add_u64 v[12:13], v[34:35], 1, s[42:43]
	s_waitcnt lgkmcnt(0)
	v_add_f32_e32 v2, v2, v3
	ds_bpermute_b32 v3, v135, v2
	s_nop 0
	v_pk_mul_f32 v[6:7], v[232:233], v[6:7]
	v_pk_mul_f32 v[4:5], v[230:231], v[4:5]
	s_nop 0
	v_cvt_pk_f16_f32 v4, v4, v5
	v_cvt_pk_f16_f32 v5, v6, v7
	global_store_dwordx2 v[12:13], v[4:5], off
	s_and_saveexec_b64 s[4:5], vcc
	s_cbranch_execz .LBB0_1243
	v_lshlrev_b32_e32 v0, 2, v0
	s_waitcnt lgkmcnt(0)
	v_add_f32_e32 v2, v2, v3
	global_atomic_add_f32 v0, v2, s[12:13]
	s_branch .LBB0_1243
